# EpiKV epilogue (both layers): all 16 partial-sum loads of the 8 row steps issued up front with counted waits instead of load-after-byte-stores + vmcnt(0) per step
# speedup vs baseline: 1.0038x; 1.0038x over previous
.LBB0_631:
	v_mov_b32_e32 v136, v0
	s_lshl_b32 s9, s6, 8
	v_readlane_b32 s6, v254, 48
	s_add_i32 s9, s9, s6
	v_and_b32_e32 v34, 15, v136
	v_or_b32_e32 v146, s9, v34
	v_ashrrev_i32_e32 v147, 31, v146
	v_lshlrev_b64 v[138:139], 5, v[146:147]
	v_lshl_add_u64 v[144:145], s[20:21], 0, v[138:139]
	global_load_dwordx4 v[138:141], v[144:145], off
	global_load_dwordx4 v[156:159], v[144:145], off offset:16
	s_mov_b32 s100, 0x1000
	s_mov_b32 s101, 0
	v_lshl_add_u64 v[250:251], v[144:145], 0, s[100:101]
	global_load_dwordx4 v[172:175], v[144:145], off offset:512
	global_load_dwordx4 v[176:179], v[144:145], off offset:528
	global_load_dwordx4 v[180:183], v[144:145], off offset:1024
	global_load_dwordx4 v[184:187], v[144:145], off offset:1040
	global_load_dwordx4 v[188:191], v[144:145], off offset:1536
	global_load_dwordx4 v[192:195], v[144:145], off offset:1552
	global_load_dwordx4 v[196:199], v[250:251], off
	global_load_dwordx4 v[200:203], v[250:251], off offset:16
	global_load_dwordx4 v[204:207], v[250:251], off offset:512
	global_load_dwordx4 v[208:211], v[250:251], off offset:528
	global_load_dwordx4 v[224:227], v[250:251], off offset:1024
	global_load_dwordx4 v[228:231], v[250:251], off offset:1040
	global_load_dwordx4 v[232:235], v[250:251], off offset:1536
	global_load_dwordx4 v[236:239], v[250:251], off offset:1552
	s_lshl_b32 s90, s7, 7
	v_bfe_u32 v155, v136, 4, 2
	v_lshl_or_b32 v136, v155, 3, s90
	v_or_b32_e32 v136, s30, v136
	v_ashrrev_i32_e32 v137, 31, v136
	v_lshlrev_b64 v[136:137], 14, v[136:137]
	v_or_b32_e32 v148, 16, v146
	v_ashrrev_i32_e32 v149, 31, v148
	v_lshlrev_b64 v[148:149], 5, v[148:149]
	v_lshl_add_u64 v[148:149], s[20:21], 0, v[148:149]
	v_permlane32_swap_b32_e32 v2, v18
	v_permlane32_swap_b32_e32 v3, v19
	v_permlane32_swap_b32_e32 v10, v26
	v_permlane32_swap_b32_e32 v11, v27
	v_permlane32_swap_b32_e32 v4, v20
	v_permlane32_swap_b32_e32 v5, v21
	v_permlane32_swap_b32_e32 v6, v22
	v_permlane32_swap_b32_e32 v7, v23
	v_permlane32_swap_b32_e32 v8, v24
	v_permlane32_swap_b32_e32 v9, v25
	v_permlane32_swap_b32_e32 v12, v28
	v_permlane32_swap_b32_e32 v13, v29
	v_permlane32_swap_b32_e32 v14, v30
	v_permlane32_swap_b32_e32 v15, v31
	v_permlane32_swap_b32_e32 v16, v32
	v_permlane32_swap_b32_e32 v17, v33
	v_permlane16_swap_b32_e32 v2, v10
	v_permlane16_swap_b32_e32 v3, v11
	v_permlane16_swap_b32_e32 v18, v26
	v_permlane16_swap_b32_e32 v19, v27
	v_permlane16_swap_b32_e32 v4, v12
	v_permlane16_swap_b32_e32 v5, v13
	v_permlane16_swap_b32_e32 v6, v14
	v_permlane16_swap_b32_e32 v7, v15
	v_permlane16_swap_b32_e32 v8, v16
	v_permlane16_swap_b32_e32 v9, v17
	v_permlane16_swap_b32_e32 v20, v28
	v_permlane16_swap_b32_e32 v21, v29
	v_permlane16_swap_b32_e32 v22, v30
	v_permlane16_swap_b32_e32 v23, v31
	v_permlane16_swap_b32_e32 v24, v32
	v_permlane16_swap_b32_e32 v25, v33
	s_ashr_i32 s91, s90, 31
	v_permlane32_swap_b32_e32 v36, v40
	v_permlane32_swap_b32_e32 v37, v41
	s_waitcnt vmcnt(14)
	v_pk_add_f32 v[140:141], v[140:141], v[158:159]
	v_pk_add_f32 v[138:139], v[138:139], v[156:157]
	v_permlane32_swap_b32_e32 v38, v42
	v_pk_mov_b32 v[142:143], v[138:139], v[140:141] op_sel:[1,0]
	v_mov_b32_e32 v139, v141
	v_pk_add_f32 v[138:139], v[142:143], v[138:139]
	v_permlane32_swap_b32_e32 v39, v43
	v_add_f32_e32 v138, v138, v139
	v_fmamk_f32 v138, v138, 0x3b800000, v153
	v_cmp_gt_f32_e32 vcc, s24, v138
	v_mul_f32_e32 v139, 0x4f800000, v138
	v_permlane32_swap_b32_e32 v44, v48
	v_cndmask_b32_e32 v138, v138, v139, vcc
	v_sqrt_f32_e32 v139, v138
	v_permlane32_swap_b32_e32 v45, v49
	v_permlane32_swap_b32_e32 v46, v50
	v_add_u32_e32 v140, -1, v139
	v_fma_f32 v141, -v140, v139, v138
	v_cmp_ge_f32_e64 s[6:7], 0, v141
	v_add_u32_e32 v141, 1, v139
	v_permlane32_swap_b32_e32 v47, v51
	v_cndmask_b32_e64 v140, v139, v140, s[6:7]
	v_fma_f32 v139, -v141, v139, v138
	v_cmp_lt_f32_e64 s[6:7], 0, v139
	v_permlane32_swap_b32_e32 v52, v56
	s_nop 0
	v_cndmask_b32_e64 v139, v140, v141, s[6:7]
	v_mul_f32_e32 v140, 0x37800000, v139
	v_cndmask_b32_e32 v139, v139, v140, vcc
	v_cmp_class_f32_e32 vcc, v138, v154
	v_permlane32_swap_b32_e32 v53, v57
	s_nop 0
	v_cndmask_b32_e32 v138, v139, v138, vcc
	v_div_scale_f32 v139, s[6:7], v138, v138, 1.0
	v_rcp_f32_e32 v140, v139
	s_mov_b32 s6, 0x10000
	v_permlane32_swap_b32_e32 v54, v58
	v_fma_f32 v141, -v139, v140, 1.0
	v_fmac_f32_e32 v140, v141, v140
	v_div_scale_f32 v141, vcc, 1.0, v138, 1.0
	v_mul_f32_e32 v142, v141, v140
	v_fma_f32 v143, -v139, v142, v141
	v_fmac_f32_e32 v142, v143, v140
	v_fma_f32 v139, -v139, v142, v141
	v_div_fmas_f32 v139, v139, v140, v142
	v_div_fixup_f32 v138, v139, v138, 1.0
	v_pk_mul_f32 v[124:125], v[124:125], v[138:139] op_sel_hi:[1,0]
	v_mov_b32_e32 v140, 0
	v_cvt_pk_fp8_f32 v140, v124, v125
	v_pk_mul_f32 v[128:129], v[128:129], v[138:139] op_sel_hi:[1,0]
	v_mov_b32_e32 v142, 0
	v_cvt_pk_fp8_f32 v142, v128, v129
	v_pk_mul_f32 v[126:127], v[126:127], v[138:139] op_sel_hi:[1,0]
	v_lshl_add_u64 v[124:125], s[22:23], 0, v[136:137]
	v_cvt_pk_fp8_f32 v140, v126, v127 op_sel:[0,0,1]
	v_lshl_add_u64 v[124:125], v[124:125], 0, v[146:147]
	v_pk_mul_f32 v[130:131], v[130:131], v[138:139] op_sel_hi:[1,0]
	v_add_co_u32_e32 v126, vcc, s6, v124
	v_cvt_pk_fp8_f32 v142, v130, v131 op_sel:[0,0,1]
	s_nop 0
	v_addc_co_u32_e32 v127, vcc, 0, v125, vcc
	s_movk_i32 s6, 0x4000
	v_add_co_u32_e32 v128, vcc, s6, v124
	v_lshrrev_b32_e32 v130, 8, v140
	s_nop 0
	v_addc_co_u32_e32 v129, vcc, 0, v125, vcc
	s_mov_b32 s6, 0x14000
	global_store_byte v[128:129], v130, off
	v_add_co_u32_e32 v130, vcc, s6, v124
	v_lshrrev_b32_e32 v136, 8, v142
	s_nop 0
	v_addc_co_u32_e32 v131, vcc, 0, v125, vcc
	s_mov_b32 s6, 0x8000
	global_store_byte v[130:131], v136, off
	v_add_co_u32_e32 v136, vcc, s6, v124
	s_mov_b32 s6, 0x18000
	s_nop 0
	v_addc_co_u32_e32 v137, vcc, 0, v125, vcc
	v_add_co_u32_e32 v138, vcc, s6, v124
	s_mov_b32 s6, 0xc000
	s_nop 0
	v_addc_co_u32_e32 v139, vcc, 0, v125, vcc
	global_store_byte v[124:125], v140, off
	global_store_byte_d16_hi v[136:137], v140, off
	v_lshrrev_b32_e32 v143, 24, v140
	v_add_co_u32_e32 v140, vcc, s6, v124
	s_mov_b32 s6, 0x1c000
	s_nop 0
	v_addc_co_u32_e32 v141, vcc, 0, v125, vcc
	global_store_byte v[126:127], v142, off
	global_store_byte_d16_hi v[138:139], v142, off
	v_lshrrev_b32_e32 v147, 24, v142
	v_add_co_u32_e32 v142, vcc, s6, v124
	global_store_byte v[140:141], v143, off
	s_nop 0
	v_addc_co_u32_e32 v143, vcc, 0, v125, vcc
	global_store_byte v[142:143], v147, off
	v_permlane32_swap_b32_e32 v55, v59
	v_permlane32_swap_b32_e32 v60, v64
	v_permlane32_swap_b32_e32 v61, v65
	v_permlane32_swap_b32_e32 v62, v66
	v_permlane32_swap_b32_e32 v63, v67
	v_permlane16_swap_b32_e32 v36, v52
	v_permlane16_swap_b32_e32 v37, v53
	v_permlane16_swap_b32_e32 v38, v54
	v_permlane16_swap_b32_e32 v39, v55
	v_permlane16_swap_b32_e32 v44, v60
	v_permlane16_swap_b32_e32 v45, v61
	v_permlane16_swap_b32_e32 v46, v62
	v_permlane16_swap_b32_e32 v47, v63
	v_permlane16_swap_b32_e32 v40, v56
	v_permlane16_swap_b32_e32 v41, v57
	v_permlane16_swap_b32_e32 v42, v58
	v_permlane16_swap_b32_e32 v43, v59
	v_permlane16_swap_b32_e32 v48, v64
	v_permlane16_swap_b32_e32 v49, v65
	v_permlane16_swap_b32_e32 v50, v66
	v_permlane16_swap_b32_e32 v51, v67
	s_cmp_eq_u32 s0, s50
	v_readlane_b32 s96, v254, 46
	v_readlane_b32 s97, v254, 47
	s_waitcnt vmcnt(20)
	v_pk_add_f32 v[148:149], v[174:175], v[178:179]
	v_pk_add_f32 v[156:157], v[172:173], v[176:177]
	s_nop 0
	v_pk_mov_b32 v[158:159], v[156:157], v[148:149] op_sel:[1,0]
	v_mov_b32_e32 v157, v149
	v_pk_add_f32 v[148:149], v[158:159], v[156:157]
	s_nop 0
	v_add_f32_e32 v147, v148, v149
	v_fmamk_f32 v147, v147, 0x3b800000, v153
	v_cmp_gt_f32_e32 vcc, s24, v147
	v_mul_f32_e32 v148, 0x4f800000, v147
	s_nop 0
	v_cndmask_b32_e32 v147, v147, v148, vcc
	v_sqrt_f32_e32 v148, v147
	s_nop 0
	v_add_u32_e32 v149, -1, v148
	v_fma_f32 v156, -v149, v148, v147
	v_cmp_ge_f32_e64 s[6:7], 0, v156
	v_add_u32_e32 v156, 1, v148
	s_nop 0
	v_cndmask_b32_e64 v149, v148, v149, s[6:7]
	v_fma_f32 v148, -v156, v148, v147
	v_cmp_lt_f32_e64 s[6:7], 0, v148
	s_nop 1
	v_cndmask_b32_e64 v148, v149, v156, s[6:7]
	v_mul_f32_e32 v149, 0x37800000, v148
	v_cndmask_b32_e32 v148, v148, v149, vcc
	v_cmp_class_f32_e32 vcc, v147, v154
	s_nop 1
	v_cndmask_b32_e32 v147, v148, v147, vcc
	v_div_scale_f32 v148, s[6:7], v147, v147, 1.0
	v_rcp_f32_e32 v149, v148
	s_nop 0
	v_fma_f32 v156, -v148, v149, 1.0
	v_fmac_f32_e32 v149, v156, v149
	v_div_scale_f32 v156, vcc, 1.0, v147, 1.0
	v_mul_f32_e32 v157, v156, v149
	v_fma_f32 v158, -v148, v157, v156
	v_fmac_f32_e32 v157, v158, v149
	v_fma_f32 v148, -v148, v157, v156
	v_div_fmas_f32 v148, v148, v149, v157
	v_div_fixup_f32 v148, v148, v147, 1.0
	v_pk_mul_f32 v[116:117], v[116:117], v[148:149] op_sel_hi:[1,0]
	v_mov_b32_e32 v147, 0
	v_pk_mul_f32 v[120:121], v[120:121], v[148:149] op_sel_hi:[1,0]
	v_cvt_pk_fp8_f32 v147, v116, v117
	v_mov_b32_e32 v116, 0
	v_cvt_pk_fp8_f32 v116, v120, v121
	v_pk_mul_f32 v[118:119], v[118:119], v[148:149] op_sel_hi:[1,0]
	v_pk_mul_f32 v[122:123], v[122:123], v[148:149] op_sel_hi:[1,0]
	v_cvt_pk_fp8_f32 v147, v118, v119 op_sel:[0,0,1]
	v_cvt_pk_fp8_f32 v116, v122, v123 op_sel:[0,0,1]
	global_store_byte v[124:125], v147, off offset:16
	global_store_byte v[126:127], v116, off offset:16
	v_lshrrev_b32_e32 v117, 8, v147
	global_store_byte v[128:129], v117, off offset:16
	v_lshrrev_b32_e32 v117, 8, v116
	global_store_byte v[130:131], v117, off offset:16
	global_store_byte_d16_hi v[136:137], v147, off offset:16
	global_store_byte_d16_hi v[138:139], v116, off offset:16
	v_lshrrev_b32_e32 v116, 24, v116
	v_lshrrev_b32_e32 v117, 24, v147
	global_store_byte v[142:143], v116, off offset:16
	v_or_b32_e32 v116, 32, v146
	global_store_byte v[140:141], v117, off offset:16
	v_ashrrev_i32_e32 v117, 31, v116
	v_lshlrev_b64 v[116:117], 5, v[116:117]
	v_lshl_add_u64 v[120:121], s[20:21], 0, v[116:117]
	s_nop 0
	s_waitcnt vmcnt(26)
	v_pk_add_f32 v[118:119], v[182:183], v[186:187]
	v_pk_add_f32 v[116:117], v[180:181], v[184:185]
	s_nop 0
	v_pk_mov_b32 v[120:121], v[116:117], v[118:119] op_sel:[1,0]
	v_mov_b32_e32 v117, v119
	v_pk_add_f32 v[116:117], v[120:121], v[116:117]
	s_nop 0
	v_add_f32_e32 v116, v116, v117
	v_fmamk_f32 v116, v116, 0x3b800000, v153
	v_cmp_gt_f32_e32 vcc, s24, v116
	v_mul_f32_e32 v117, 0x4f800000, v116
	s_nop 0
	v_cndmask_b32_e32 v116, v116, v117, vcc
	v_sqrt_f32_e32 v117, v116
	s_nop 0
	v_add_u32_e32 v118, -1, v117
	v_fma_f32 v119, -v118, v117, v116
	v_cmp_ge_f32_e64 s[6:7], 0, v119
	v_add_u32_e32 v119, 1, v117
	s_nop 0
	v_cndmask_b32_e64 v118, v117, v118, s[6:7]
	v_fma_f32 v117, -v119, v117, v116
	v_cmp_lt_f32_e64 s[6:7], 0, v117
	s_nop 1
	v_cndmask_b32_e64 v117, v118, v119, s[6:7]
	v_mul_f32_e32 v118, 0x37800000, v117
	v_cndmask_b32_e32 v117, v117, v118, vcc
	v_cmp_class_f32_e32 vcc, v116, v154
	s_nop 1
	v_cndmask_b32_e32 v116, v117, v116, vcc
	v_div_scale_f32 v117, s[6:7], v116, v116, 1.0
	v_rcp_f32_e32 v118, v117
	s_nop 0
	v_fma_f32 v119, -v117, v118, 1.0
	v_fmac_f32_e32 v118, v119, v118
	v_div_scale_f32 v119, vcc, 1.0, v116, 1.0
	v_mul_f32_e32 v120, v119, v118
	v_fma_f32 v121, -v117, v120, v119
	v_fmac_f32_e32 v120, v121, v118
	v_fma_f32 v117, -v117, v120, v119
	v_div_fmas_f32 v117, v117, v118, v120
	v_div_fixup_f32 v116, v117, v116, 1.0
	v_pk_mul_f32 v[110:111], v[110:111], v[116:117] op_sel_hi:[1,0]
	v_pk_mul_f32 v[108:109], v[108:109], v[116:117] op_sel_hi:[1,0]
	v_pk_mul_f32 v[114:115], v[114:115], v[116:117] op_sel_hi:[1,0]
	v_pk_mul_f32 v[112:113], v[112:113], v[116:117] op_sel_hi:[1,0]
	v_mov_b32_e32 v116, 0
	v_cvt_pk_fp8_f32 v116, v108, v109
	v_mov_b32_e32 v108, 0
	v_cvt_pk_fp8_f32 v108, v112, v113
	v_cvt_pk_fp8_f32 v116, v110, v111 op_sel:[0,0,1]
	v_cvt_pk_fp8_f32 v108, v114, v115 op_sel:[0,0,1]
	global_store_byte v[124:125], v116, off offset:32
	global_store_byte v[126:127], v108, off offset:32
	v_lshrrev_b32_e32 v109, 8, v116
	global_store_byte v[128:129], v109, off offset:32
	v_lshrrev_b32_e32 v109, 8, v108
	global_store_byte v[130:131], v109, off offset:32
	global_store_byte_d16_hi v[136:137], v116, off offset:32
	global_store_byte_d16_hi v[138:139], v108, off offset:32
	v_lshrrev_b32_e32 v108, 24, v108
	v_lshrrev_b32_e32 v109, 24, v116
	global_store_byte v[142:143], v108, off offset:32
	v_or_b32_e32 v108, 48, v146
	global_store_byte v[140:141], v109, off offset:32
	v_ashrrev_i32_e32 v109, 31, v108
	v_lshlrev_b64 v[108:109], 5, v[108:109]
	v_lshl_add_u64 v[112:113], s[20:21], 0, v[108:109]
	s_nop 0
	s_waitcnt vmcnt(32)
	v_pk_add_f32 v[110:111], v[190:191], v[194:195]
	v_pk_add_f32 v[108:109], v[188:189], v[192:193]
	s_nop 0
	v_pk_mov_b32 v[112:113], v[108:109], v[110:111] op_sel:[1,0]
	v_mov_b32_e32 v109, v111
	v_pk_add_f32 v[108:109], v[112:113], v[108:109]
	s_nop 0
	v_add_f32_e32 v108, v108, v109
	v_fmamk_f32 v108, v108, 0x3b800000, v153
	v_cmp_gt_f32_e32 vcc, s24, v108
	v_mul_f32_e32 v109, 0x4f800000, v108
	s_nop 0
	v_cndmask_b32_e32 v108, v108, v109, vcc
	v_sqrt_f32_e32 v109, v108
	s_nop 0
	v_add_u32_e32 v110, -1, v109
	v_fma_f32 v111, -v110, v109, v108
	v_cmp_ge_f32_e64 s[6:7], 0, v111
	v_add_u32_e32 v111, 1, v109
	s_nop 0
	v_cndmask_b32_e64 v110, v109, v110, s[6:7]
	v_fma_f32 v109, -v111, v109, v108
	v_cmp_lt_f32_e64 s[6:7], 0, v109
	s_nop 1
	v_cndmask_b32_e64 v109, v110, v111, s[6:7]
	v_mul_f32_e32 v110, 0x37800000, v109
	v_cndmask_b32_e32 v109, v109, v110, vcc
	v_cmp_class_f32_e32 vcc, v108, v154
	s_nop 1
	v_cndmask_b32_e32 v108, v109, v108, vcc
	v_div_scale_f32 v109, s[6:7], v108, v108, 1.0
	v_rcp_f32_e32 v110, v109
	s_mov_b64 s[6:7], 0x1000
	v_fma_f32 v111, -v109, v110, 1.0
	v_fmac_f32_e32 v110, v111, v110
	v_div_scale_f32 v111, vcc, 1.0, v108, 1.0
	v_mul_f32_e32 v112, v111, v110
	v_fma_f32 v113, -v109, v112, v111
	v_fmac_f32_e32 v112, v113, v110
	v_fma_f32 v109, -v109, v112, v111
	v_div_fmas_f32 v109, v109, v110, v112
	v_div_fixup_f32 v108, v109, v108, 1.0
	v_pk_mul_f32 v[102:103], v[102:103], v[108:109] op_sel_hi:[1,0]
	v_pk_mul_f32 v[100:101], v[100:101], v[108:109] op_sel_hi:[1,0]
	v_pk_mul_f32 v[106:107], v[106:107], v[108:109] op_sel_hi:[1,0]
	v_pk_mul_f32 v[104:105], v[104:105], v[108:109] op_sel_hi:[1,0]
	v_mov_b32_e32 v108, 0
	v_cvt_pk_fp8_f32 v108, v100, v101
	v_mov_b32_e32 v100, 0
	v_cvt_pk_fp8_f32 v100, v104, v105
	v_cvt_pk_fp8_f32 v108, v102, v103 op_sel:[0,0,1]
	v_cvt_pk_fp8_f32 v100, v106, v107 op_sel:[0,0,1]
	global_store_byte v[124:125], v108, off offset:48
	global_store_byte v[126:127], v100, off offset:48
	v_lshrrev_b32_e32 v101, 8, v108
	global_store_byte v[128:129], v101, off offset:48
	v_lshrrev_b32_e32 v101, 8, v100
	global_store_byte v[130:131], v101, off offset:48
	global_store_byte_d16_hi v[136:137], v108, off offset:48
	global_store_byte_d16_hi v[138:139], v100, off offset:48
	v_lshrrev_b32_e32 v100, 24, v100
	v_lshl_add_u64 v[106:107], v[144:145], 0, s[6:7]
	s_movk_i32 s6, 0x1000
	v_lshrrev_b32_e32 v101, 24, v108
	global_store_byte v[142:143], v100, off offset:48
	v_add_co_u32_e32 v100, vcc, s6, v144
	global_store_byte v[140:141], v101, off offset:48
	s_nop 0
	v_addc_co_u32_e32 v101, vcc, 0, v145, vcc
	s_nop 0
	s_waitcnt vmcnt(38)
	v_pk_add_f32 v[104:105], v[198:199], v[202:203]
	v_pk_add_f32 v[102:103], v[196:197], v[200:201]
	s_nop 0
	v_pk_mov_b32 v[106:107], v[102:103], v[104:105] op_sel:[1,0]
	v_mov_b32_e32 v103, v105
	v_pk_add_f32 v[102:103], v[106:107], v[102:103]
	s_nop 0
	v_add_f32_e32 v102, v102, v103
	v_fmamk_f32 v102, v102, 0x3b800000, v153
	v_cmp_gt_f32_e32 vcc, s24, v102
	v_mul_f32_e32 v103, 0x4f800000, v102
	s_nop 0
	v_cndmask_b32_e32 v102, v102, v103, vcc
	v_sqrt_f32_e32 v103, v102
	s_nop 0
	v_add_u32_e32 v104, -1, v103
	v_fma_f32 v105, -v104, v103, v102
	v_cmp_ge_f32_e64 s[6:7], 0, v105
	v_add_u32_e32 v105, 1, v103
	s_nop 0
	v_cndmask_b32_e64 v104, v103, v104, s[6:7]
	v_fma_f32 v103, -v105, v103, v102
	v_cmp_lt_f32_e64 s[6:7], 0, v103
	s_nop 1
	v_cndmask_b32_e64 v103, v104, v105, s[6:7]
	v_mul_f32_e32 v104, 0x37800000, v103
	v_cndmask_b32_e32 v103, v103, v104, vcc
	v_cmp_class_f32_e32 vcc, v102, v154
	s_nop 1
	v_cndmask_b32_e32 v102, v103, v102, vcc
	v_div_scale_f32 v103, s[6:7], v102, v102, 1.0
	v_rcp_f32_e32 v104, v103
	s_mov_b64 s[6:7], 0x1200
	v_fma_f32 v105, -v103, v104, 1.0
	v_fmac_f32_e32 v104, v105, v104
	v_div_scale_f32 v105, vcc, 1.0, v102, 1.0
	v_mul_f32_e32 v106, v105, v104
	v_fma_f32 v107, -v103, v106, v105
	v_fmac_f32_e32 v106, v107, v104
	v_fma_f32 v103, -v103, v106, v105
	v_div_fmas_f32 v103, v103, v104, v106
	v_div_fixup_f32 v102, v103, v102, 1.0
	v_pk_mul_f32 v[104:105], v[92:93], v[102:103] op_sel_hi:[1,0]
	v_pk_mul_f32 v[92:93], v[98:99], v[102:103] op_sel_hi:[1,0]
	v_mov_b32_e32 v98, 0
	v_cvt_pk_fp8_f32 v98, v104, v105
	v_pk_mul_f32 v[94:95], v[94:95], v[102:103] op_sel_hi:[1,0]
	v_pk_mul_f32 v[96:97], v[96:97], v[102:103] op_sel_hi:[1,0]
	v_cvt_pk_fp8_f32 v98, v94, v95 op_sel:[0,0,1]
	v_mov_b32_e32 v94, 0
	v_cvt_pk_fp8_f32 v94, v96, v97
	v_lshl_add_u64 v[96:97], v[144:145], 0, s[6:7]
	v_cvt_pk_fp8_f32 v94, v92, v93 op_sel:[0,0,1]
	v_lshrrev_b32_e32 v92, 8, v98
	global_store_byte v[124:125], v98, off offset:128
	global_store_byte v[126:127], v94, off offset:128
	global_store_byte v[128:129], v92, off offset:128
	v_lshrrev_b32_e32 v92, 8, v94
	global_store_byte v[130:131], v92, off offset:128
	global_store_byte_d16_hi v[136:137], v98, off offset:128
	global_store_byte_d16_hi v[138:139], v94, off offset:128
	v_lshrrev_b32_e32 v92, 24, v98
	global_store_byte v[140:141], v92, off offset:128
	v_lshrrev_b32_e32 v92, 24, v94
	global_store_byte v[142:143], v92, off offset:128
	s_nop 0
	s_waitcnt vmcnt(44)
	v_pk_add_f32 v[94:95], v[206:207], v[210:211]
	v_pk_add_f32 v[92:93], v[204:205], v[208:209]
	s_nop 0
	v_pk_mov_b32 v[96:97], v[92:93], v[94:95] op_sel:[1,0]
	v_mov_b32_e32 v93, v95
	v_pk_add_f32 v[92:93], v[96:97], v[92:93]
	s_nop 0
	v_add_f32_e32 v92, v92, v93
	v_fmamk_f32 v92, v92, 0x3b800000, v153
	v_cmp_gt_f32_e32 vcc, s24, v92
	v_mul_f32_e32 v93, 0x4f800000, v92
	s_nop 0
	v_cndmask_b32_e32 v92, v92, v93, vcc
	v_sqrt_f32_e32 v93, v92
	s_nop 0
	v_add_u32_e32 v94, -1, v93
	v_fma_f32 v95, -v94, v93, v92
	v_cmp_ge_f32_e64 s[6:7], 0, v95
	v_add_u32_e32 v95, 1, v93
	s_nop 0
	v_cndmask_b32_e64 v94, v93, v94, s[6:7]
	v_fma_f32 v93, -v95, v93, v92
	v_cmp_lt_f32_e64 s[6:7], 0, v93
	s_nop 1
	v_cndmask_b32_e64 v93, v94, v95, s[6:7]
	v_mul_f32_e32 v94, 0x37800000, v93
	v_cndmask_b32_e32 v93, v93, v94, vcc
	v_cmp_class_f32_e32 vcc, v92, v154
	s_nop 1
	v_cndmask_b32_e32 v92, v93, v92, vcc
	v_div_scale_f32 v93, s[6:7], v92, v92, 1.0
	v_rcp_f32_e32 v94, v93
	s_mov_b64 s[6:7], 0x1400
	v_fma_f32 v95, -v93, v94, 1.0
	v_fmac_f32_e32 v94, v95, v94
	v_div_scale_f32 v95, vcc, 1.0, v92, 1.0
	v_mul_f32_e32 v96, v95, v94
	v_fma_f32 v97, -v93, v96, v95
	v_fmac_f32_e32 v96, v97, v94
	v_fma_f32 v93, -v93, v96, v95
	v_div_fmas_f32 v93, v93, v94, v96
	v_div_fixup_f32 v92, v93, v92, 1.0
	v_pk_mul_f32 v[94:95], v[84:85], v[92:93] op_sel_hi:[1,0]
	v_pk_mul_f32 v[84:85], v[90:91], v[92:93] op_sel_hi:[1,0]
	v_mov_b32_e32 v90, 0
	v_cvt_pk_fp8_f32 v90, v94, v95
	v_pk_mul_f32 v[86:87], v[86:87], v[92:93] op_sel_hi:[1,0]
	v_pk_mul_f32 v[88:89], v[88:89], v[92:93] op_sel_hi:[1,0]
	v_cvt_pk_fp8_f32 v90, v86, v87 op_sel:[0,0,1]
	v_mov_b32_e32 v86, 0
	v_cvt_pk_fp8_f32 v86, v88, v89
	v_lshl_add_u64 v[88:89], v[144:145], 0, s[6:7]
	v_cvt_pk_fp8_f32 v86, v84, v85 op_sel:[0,0,1]
	v_lshrrev_b32_e32 v84, 8, v90
	global_store_byte v[124:125], v90, off offset:144
	global_store_byte v[126:127], v86, off offset:144
	global_store_byte v[128:129], v84, off offset:144
	v_lshrrev_b32_e32 v84, 8, v86
	global_store_byte v[130:131], v84, off offset:144
	global_store_byte_d16_hi v[136:137], v90, off offset:144
	global_store_byte_d16_hi v[138:139], v86, off offset:144
	v_lshrrev_b32_e32 v84, 24, v90
	global_store_byte v[140:141], v84, off offset:144
	v_lshrrev_b32_e32 v84, 24, v86
	global_store_byte v[142:143], v84, off offset:144
	s_nop 0
	s_waitcnt vmcnt(50)
	v_pk_add_f32 v[86:87], v[226:227], v[230:231]
	v_pk_add_f32 v[84:85], v[224:225], v[228:229]
	s_nop 0
	v_pk_mov_b32 v[88:89], v[84:85], v[86:87] op_sel:[1,0]
	v_mov_b32_e32 v85, v87
	v_pk_add_f32 v[84:85], v[88:89], v[84:85]
	s_nop 0
	v_add_f32_e32 v84, v84, v85
	v_fmamk_f32 v84, v84, 0x3b800000, v153
	v_cmp_gt_f32_e32 vcc, s24, v84
	v_mul_f32_e32 v85, 0x4f800000, v84
	s_nop 0
	v_cndmask_b32_e32 v84, v84, v85, vcc
	v_sqrt_f32_e32 v85, v84
	s_nop 0
	v_add_u32_e32 v86, -1, v85
	v_fma_f32 v87, -v86, v85, v84
	v_cmp_ge_f32_e64 s[6:7], 0, v87
	v_add_u32_e32 v87, 1, v85
	s_nop 0
	v_cndmask_b32_e64 v86, v85, v86, s[6:7]
	v_fma_f32 v85, -v87, v85, v84
	v_cmp_lt_f32_e64 s[6:7], 0, v85
	s_nop 1
	v_cndmask_b32_e64 v85, v86, v87, s[6:7]
	v_mul_f32_e32 v86, 0x37800000, v85
	v_cndmask_b32_e32 v85, v85, v86, vcc
	v_cmp_class_f32_e32 vcc, v84, v154
	s_nop 1
	v_cndmask_b32_e32 v84, v85, v84, vcc
	v_div_scale_f32 v85, s[6:7], v84, v84, 1.0
	v_rcp_f32_e32 v86, v85
	s_mov_b64 s[6:7], 0x1600
	v_fma_f32 v87, -v85, v86, 1.0
	v_fmac_f32_e32 v86, v87, v86
	v_div_scale_f32 v87, vcc, 1.0, v84, 1.0
	v_mul_f32_e32 v88, v87, v86
	v_fma_f32 v89, -v85, v88, v87
	v_fmac_f32_e32 v88, v89, v86
	v_fma_f32 v85, -v85, v88, v87
	v_div_fmas_f32 v85, v85, v86, v88
	v_div_fixup_f32 v84, v85, v84, 1.0
	v_pk_mul_f32 v[86:87], v[76:77], v[84:85] op_sel_hi:[1,0]
	v_pk_mul_f32 v[76:77], v[82:83], v[84:85] op_sel_hi:[1,0]
	v_mov_b32_e32 v82, 0
	v_cvt_pk_fp8_f32 v82, v86, v87
	v_pk_mul_f32 v[78:79], v[78:79], v[84:85] op_sel_hi:[1,0]
	v_pk_mul_f32 v[80:81], v[80:81], v[84:85] op_sel_hi:[1,0]
	v_cvt_pk_fp8_f32 v82, v78, v79 op_sel:[0,0,1]
	v_mov_b32_e32 v78, 0
	v_cvt_pk_fp8_f32 v78, v80, v81
	v_lshl_add_u64 v[80:81], v[144:145], 0, s[6:7]
	v_cvt_pk_fp8_f32 v78, v76, v77 op_sel:[0,0,1]
	v_lshrrev_b32_e32 v76, 8, v82
	global_store_byte v[124:125], v82, off offset:160
	global_store_byte v[126:127], v78, off offset:160
	global_store_byte v[128:129], v76, off offset:160
	v_lshrrev_b32_e32 v76, 8, v78
	global_store_byte v[130:131], v76, off offset:160
	global_store_byte_d16_hi v[136:137], v82, off offset:160
	global_store_byte_d16_hi v[138:139], v78, off offset:160
	v_lshrrev_b32_e32 v76, 24, v82
	global_store_byte v[140:141], v76, off offset:160
	v_lshrrev_b32_e32 v76, 24, v78
	global_store_byte v[142:143], v76, off offset:160
	s_nop 0
	s_waitcnt vmcnt(56)
	v_pk_add_f32 v[78:79], v[234:235], v[238:239]
	v_pk_add_f32 v[76:77], v[232:233], v[236:237]
	s_nop 0
	v_pk_mov_b32 v[80:81], v[76:77], v[78:79] op_sel:[1,0]
	v_mov_b32_e32 v77, v79
	v_pk_add_f32 v[76:77], v[80:81], v[76:77]
	s_nop 0
	v_add_f32_e32 v76, v76, v77
	v_fmamk_f32 v76, v76, 0x3b800000, v153
	v_cmp_gt_f32_e32 vcc, s24, v76
	v_mul_f32_e32 v77, 0x4f800000, v76
	s_nop 0
	v_cndmask_b32_e32 v76, v76, v77, vcc
	v_sqrt_f32_e32 v77, v76
	s_nop 0
	v_add_u32_e32 v78, -1, v77
	v_fma_f32 v79, -v78, v77, v76
	v_cmp_ge_f32_e64 s[6:7], 0, v79
	v_add_u32_e32 v79, 1, v77
	s_nop 0
	v_cndmask_b32_e64 v78, v77, v78, s[6:7]
	v_fma_f32 v77, -v79, v77, v76
	v_cmp_lt_f32_e64 s[6:7], 0, v77
	s_nop 1
	v_cndmask_b32_e64 v77, v78, v79, s[6:7]
	v_mul_f32_e32 v78, 0x37800000, v77
	v_cndmask_b32_e32 v77, v77, v78, vcc
	v_cmp_class_f32_e32 vcc, v76, v154
	s_nop 1
	v_cndmask_b32_e32 v76, v77, v76, vcc
	v_div_scale_f32 v77, s[6:7], v76, v76, 1.0
	v_rcp_f32_e32 v78, v77
	s_nop 0
	v_fma_f32 v79, -v77, v78, 1.0
	v_fmac_f32_e32 v78, v79, v78
	v_div_scale_f32 v79, vcc, 1.0, v76, 1.0
	v_mul_f32_e32 v80, v79, v78
	v_fma_f32 v81, -v77, v80, v79
	v_fmac_f32_e32 v80, v81, v78
	v_fma_f32 v77, -v77, v80, v79
	v_div_fmas_f32 v77, v77, v78, v80
	v_div_fixup_f32 v76, v77, v76, 1.0
	v_pk_mul_f32 v[70:71], v[70:71], v[76:77] op_sel_hi:[1,0]
	v_pk_mul_f32 v[68:69], v[68:69], v[76:77] op_sel_hi:[1,0]
	v_pk_mul_f32 v[74:75], v[74:75], v[76:77] op_sel_hi:[1,0]
	v_pk_mul_f32 v[72:73], v[72:73], v[76:77] op_sel_hi:[1,0]
	v_mov_b32_e32 v76, 0
	v_cvt_pk_fp8_f32 v76, v68, v69
	v_mov_b32_e32 v68, 0
	v_cvt_pk_fp8_f32 v68, v72, v73
	v_cvt_pk_fp8_f32 v76, v70, v71 op_sel:[0,0,1]
	v_cvt_pk_fp8_f32 v68, v74, v75 op_sel:[0,0,1]
	global_store_byte v[124:125], v76, off offset:176
	global_store_byte v[126:127], v68, off offset:176
	v_lshrrev_b32_e32 v69, 8, v76
	global_store_byte v[128:129], v69, off offset:176
	v_lshrrev_b32_e32 v69, 8, v68
	global_store_byte v[130:131], v69, off offset:176
	global_store_byte_d16_hi v[136:137], v76, off offset:176
	global_store_byte_d16_hi v[138:139], v68, off offset:176
	v_lshrrev_b32_e32 v68, 24, v68
	global_store_byte v[142:143], v68, off offset:176
	v_lshlrev_b32_e32 v68, 4, v155
	v_lshrrev_b32_e32 v69, 24, v76
	v_or3_b32 v68, v68, s9, v34
	global_store_byte v[140:141], v69, off offset:176
	v_ashrrev_i32_e32 v69, 31, v68
	v_lshlrev_b64 v[70:71], 5, v[68:69]
	v_lshl_add_u64 v[74:75], s[20:21], 0, v[70:71]
	global_load_dwordx4 v[70:73], v[74:75], off
	s_nop 0
	global_load_dwordx4 v[74:77], v[74:75], off offset:16
	s_waitcnt vmcnt(0)
	v_pk_add_f32 v[72:73], v[72:73], v[76:77]
	v_pk_add_f32 v[70:71], v[70:71], v[74:75]
	s_nop 0
	v_pk_mov_b32 v[74:75], v[70:71], v[72:73] op_sel:[1,0]
	v_mov_b32_e32 v71, v73
	v_pk_add_f32 v[70:71], v[74:75], v[70:71]
	s_nop 0
	v_add_f32_e32 v34, v70, v71
	v_fmamk_f32 v34, v34, 0x3b800000, v153
	v_cmp_gt_f32_e32 vcc, s24, v34
	v_mul_f32_e32 v70, 0x4f800000, v34
	s_nop 0
	v_cndmask_b32_e32 v34, v34, v70, vcc
	v_sqrt_f32_e32 v70, v34
	s_nop 0
	v_add_u32_e32 v71, -1, v70
	v_fma_f32 v72, -v71, v70, v34
	v_cmp_ge_f32_e64 s[6:7], 0, v72
	v_add_u32_e32 v72, 1, v70
	s_nop 0
	v_cndmask_b32_e64 v71, v70, v71, s[6:7]
	v_fma_f32 v70, -v72, v70, v34
	v_cmp_lt_f32_e64 s[6:7], 0, v70
	s_nop 1
	v_cndmask_b32_e64 v70, v71, v72, s[6:7]
	v_mul_f32_e32 v71, 0x37800000, v70
	v_cndmask_b32_e32 v70, v70, v71, vcc
	v_cmp_class_f32_e32 vcc, v34, v154
	s_nop 1
	v_cndmask_b32_e32 v34, v70, v34, vcc
	v_div_scale_f32 v70, s[6:7], v34, v34, 1.0
	v_rcp_f32_e32 v71, v70
	s_nop 0
	v_fma_f32 v72, -v70, v71, 1.0
	v_fmac_f32_e32 v71, v72, v71
	v_div_scale_f32 v72, vcc, 1.0, v34, 1.0
	v_mul_f32_e32 v73, v72, v71
	v_fma_f32 v74, -v70, v73, v72
	v_fmac_f32_e32 v73, v74, v71
	v_fma_f32 v70, -v70, v73, v72
	v_div_fmas_f32 v70, v70, v71, v73
	v_div_fixup_f32 v34, v70, v34, 1.0
	v_pk_mul_f32 v[2:3], v[34:35], v[2:3] op_sel_hi:[0,1]
	v_pk_mul_f32 v[18:19], v[34:35], v[18:19] op_sel_hi:[0,1]
	v_pk_mul_f32 v[16:17], v[34:35], v[16:17] op_sel_hi:[0,1]
	v_pk_mul_f32 v[14:15], v[34:35], v[14:15] op_sel_hi:[0,1]
	v_pk_mul_f32 v[12:13], v[34:35], v[12:13] op_sel_hi:[0,1]
	v_pk_mul_f32 v[10:11], v[34:35], v[10:11] op_sel_hi:[0,1]
	v_pk_mul_f32 v[8:9], v[34:35], v[8:9] op_sel_hi:[0,1]
	v_pk_mul_f32 v[6:7], v[34:35], v[6:7] op_sel_hi:[0,1]
	v_pk_mul_f32 v[4:5], v[34:35], v[4:5] op_sel_hi:[0,1]
	v_pk_mul_f32 v[32:33], v[34:35], v[32:33] op_sel_hi:[0,1]
	v_pk_mul_f32 v[30:31], v[34:35], v[30:31] op_sel_hi:[0,1]
	v_pk_mul_f32 v[28:29], v[34:35], v[28:29] op_sel_hi:[0,1]
	v_pk_mul_f32 v[26:27], v[34:35], v[26:27] op_sel_hi:[0,1]
	v_pk_mul_f32 v[24:25], v[34:35], v[24:25] op_sel_hi:[0,1]
	v_pk_mul_f32 v[22:23], v[34:35], v[22:23] op_sel_hi:[0,1]
	v_pk_mul_f32 v[20:21], v[34:35], v[20:21] op_sel_hi:[0,1]
	v_max_f32_e64 v34, |v2|, |v18|
	v_max_f32_e64 v70, |v3|, |v19|
	v_max3_f32 v34, v34, 0, v70
	v_max_f32_e64 v70, |v4|, |v20|
	v_max_f32_e64 v71, |v5|, |v21|
	v_max3_f32 v34, v34, v70, v71
	v_max_f32_e64 v70, |v6|, |v22|
	v_max_f32_e64 v71, |v7|, |v23|
	v_max3_f32 v34, v34, v70, v71
	v_max_f32_e64 v70, |v8|, |v24|
	v_max_f32_e64 v71, |v9|, |v25|
	v_max3_f32 v34, v34, v70, v71
	v_max_f32_e64 v70, |v10|, |v26|
	v_max_f32_e64 v71, |v11|, |v27|
	v_max3_f32 v34, v34, v70, v71
	v_max_f32_e64 v70, |v12|, |v28|
	v_max_f32_e64 v71, |v13|, |v29|
	v_max3_f32 v34, v34, v70, v71
	v_max_f32_e64 v70, |v14|, |v30|
	v_max_f32_e64 v71, |v15|, |v31|
	v_max3_f32 v34, v34, v70, v71
	v_max_f32_e64 v70, |v16|, |v32|
	v_max_f32_e64 v71, |v17|, |v33|
	v_max3_f32 v34, v34, v70, v71
	v_bfe_u32 v70, v34, 23, 8
	v_and_b32_e32 v34, 0x7fffff, v34
	v_cmp_gt_u32_e32 vcc, s25, v34
	s_nop 1
	v_cndmask_b32_e64 v34, -2, -3, vcc
	v_add3_u32 v34, v70, v34, s40
	v_max_i32_e32 v34, 0xffffff88, v34
	v_add_u32_e32 v34, 0x7f, v34
	v_lshlrev_b32_e32 v76, 23, v34
	v_cvt_scalef32_2xpk16_fp6_f32 v[70:75], v[2:17], v[18:33], v76
	v_lshlrev_b64 v[2:3], 10, v[68:69]
	v_lshl_add_u64 v[2:3], s[26:27], 0, v[2:3]
	v_lshl_add_u64 v[2:3], v[2:3], 0, s[90:91]
	v_add_u32_e32 v68, 0x80, v68
	v_mul_lo_u32 v34, v34, s2
	v_lshl_add_u64 v[2:3], v[2:3], 0, s[30:31]
	v_mov_b32_e32 v32, v74
	v_mov_b32_e32 v33, v75
	v_ashrrev_i32_e32 v69, 31, v68
	global_store_dwordx4 v[2:3], v[70:73], off
	global_store_dwordx4 v[2:3], v[32:35], off offset:16
	v_lshlrev_b64 v[2:3], 5, v[68:69]
	v_lshl_add_u64 v[2:3], s[20:21], 0, v[2:3]
	global_load_dwordx4 v[4:7], v[2:3], off
	global_load_dwordx4 v[8:11], v[2:3], off offset:16
	s_waitcnt vmcnt(0)
	v_pk_add_f32 v[2:3], v[6:7], v[10:11]
	v_pk_add_f32 v[4:5], v[4:5], v[8:9]
	s_nop 0
	v_pk_mov_b32 v[6:7], v[4:5], v[2:3] op_sel:[1,0]
	v_mov_b32_e32 v5, v3
	v_pk_add_f32 v[2:3], v[6:7], v[4:5]
	s_nop 0
	v_add_f32_e32 v2, v2, v3
	v_fmamk_f32 v2, v2, 0x3b800000, v153
	v_cmp_gt_f32_e32 vcc, s24, v2
	v_mul_f32_e32 v3, 0x4f800000, v2
	s_nop 0
	v_cndmask_b32_e32 v2, v2, v3, vcc
	v_sqrt_f32_e32 v3, v2
	s_nop 0
	v_add_u32_e32 v4, -1, v3
	v_fma_f32 v5, -v4, v3, v2
	v_cmp_ge_f32_e64 s[6:7], 0, v5
	v_add_u32_e32 v5, 1, v3
	s_nop 0
	v_cndmask_b32_e64 v4, v3, v4, s[6:7]
	v_fma_f32 v3, -v5, v3, v2
	v_cmp_lt_f32_e64 s[6:7], 0, v3
	s_nop 1
	v_cndmask_b32_e64 v3, v4, v5, s[6:7]
	v_mul_f32_e32 v4, 0x37800000, v3
	v_cndmask_b32_e32 v3, v3, v4, vcc
	v_cmp_class_f32_e32 vcc, v2, v154
	s_nop 1
	v_cndmask_b32_e32 v2, v3, v2, vcc
	v_div_scale_f32 v3, s[6:7], v2, v2, 1.0
	v_rcp_f32_e32 v4, v3
	s_mov_b64 s[6:7], -1
	v_fma_f32 v5, -v3, v4, 1.0
	v_fmac_f32_e32 v4, v5, v4
	v_div_scale_f32 v5, vcc, 1.0, v2, 1.0
	v_mul_f32_e32 v6, v5, v4
	v_fma_f32 v7, -v3, v6, v5
	v_fmac_f32_e32 v6, v7, v4
	v_fma_f32 v3, -v3, v6, v5
	v_div_fmas_f32 v3, v3, v4, v6
	v_div_fixup_f32 v18, v3, v2, 1.0
	v_pk_mul_f32 v[16:17], v[18:19], v[62:63] op_sel_hi:[0,1]
	v_pk_mul_f32 v[14:15], v[18:19], v[60:61] op_sel_hi:[0,1]
	v_pk_mul_f32 v[12:13], v[18:19], v[54:55] op_sel_hi:[0,1]
	v_pk_mul_f32 v[10:11], v[18:19], v[52:53] op_sel_hi:[0,1]
	v_pk_mul_f32 v[8:9], v[18:19], v[46:47] op_sel_hi:[0,1]
	v_pk_mul_f32 v[6:7], v[18:19], v[44:45] op_sel_hi:[0,1]
	v_pk_mul_f32 v[4:5], v[18:19], v[38:39] op_sel_hi:[0,1]
	v_pk_mul_f32 v[2:3], v[18:19], v[36:37] op_sel_hi:[0,1]
	v_pk_mul_f32 v[32:33], v[18:19], v[66:67] op_sel_hi:[0,1]
	v_pk_mul_f32 v[30:31], v[18:19], v[64:65] op_sel_hi:[0,1]
	v_pk_mul_f32 v[28:29], v[18:19], v[58:59] op_sel_hi:[0,1]
	v_pk_mul_f32 v[26:27], v[18:19], v[56:57] op_sel_hi:[0,1]
	v_pk_mul_f32 v[24:25], v[18:19], v[50:51] op_sel_hi:[0,1]
	v_pk_mul_f32 v[22:23], v[18:19], v[48:49] op_sel_hi:[0,1]
	v_pk_mul_f32 v[20:21], v[18:19], v[42:43] op_sel_hi:[0,1]
	v_pk_mul_f32 v[18:19], v[18:19], v[40:41] op_sel_hi:[0,1]
	v_max_f32_e64 v34, |v2|, |v18|
	v_max_f32_e64 v36, |v3|, |v19|
	v_max3_f32 v34, v34, 0, v36
	v_max_f32_e64 v36, |v4|, |v20|
	v_max_f32_e64 v37, |v5|, |v21|
	v_max3_f32 v34, v34, v36, v37
	v_max_f32_e64 v36, |v6|, |v22|
	v_max_f32_e64 v37, |v7|, |v23|
	v_max3_f32 v34, v34, v36, v37
	v_max_f32_e64 v36, |v8|, |v24|
	v_max_f32_e64 v37, |v9|, |v25|
	v_max3_f32 v34, v34, v36, v37
	v_max_f32_e64 v36, |v10|, |v26|
	v_max_f32_e64 v37, |v11|, |v27|
	v_max3_f32 v34, v34, v36, v37
	v_max_f32_e64 v36, |v12|, |v28|
	v_max_f32_e64 v37, |v13|, |v29|
	v_max3_f32 v34, v34, v36, v37
	v_max_f32_e64 v36, |v14|, |v30|
	v_max_f32_e64 v37, |v15|, |v31|
	v_max3_f32 v34, v34, v36, v37
	v_max_f32_e64 v36, |v16|, |v32|
	v_max_f32_e64 v37, |v17|, |v33|
	v_max3_f32 v34, v34, v36, v37
	v_bfe_u32 v36, v34, 23, 8
	v_and_b32_e32 v34, 0x7fffff, v34
	v_cmp_gt_u32_e32 vcc, s25, v34
	s_nop 1
	v_cndmask_b32_e64 v34, -2, -3, vcc
	v_add3_u32 v34, v36, v34, s40
	v_max_i32_e32 v34, 0xffffff88, v34
	v_add_u32_e32 v34, 0x7f, v34
	v_lshlrev_b32_e32 v42, 23, v34
	v_cvt_scalef32_2xpk16_fp6_f32 v[36:41], v[2:17], v[18:33], v42
	v_lshlrev_b64 v[2:3], 10, v[68:69]
	v_lshl_add_u64 v[2:3], s[26:27], 0, v[2:3]
	v_lshl_add_u64 v[2:3], v[2:3], 0, s[90:91]
	v_mul_lo_u32 v34, v34, s2
	v_lshl_add_u64 v[2:3], v[2:3], 0, s[30:31]
	v_mov_b32_e32 v32, v40
	v_mov_b32_e32 v33, v41
	global_store_dwordx4 v[2:3], v[36:39], off
	global_store_dwordx4 v[2:3], v[32:35], off offset:16
	s_cbranch_scc1 .LBB0_626
	v_readlane_b32 s6, v254, 50
	v_readlane_b32 s7, v254, 51
	s_andn2_b64 vcc, exec, s[6:7]
	s_cbranch_vccnz .LBB0_625
	s_barrier
	s_branch .LBB0_625

.LBB0_1654:
	v_mov_b32_e32 v136, v0
	s_lshl_b32 s9, s6, 8
	v_readlane_b32 s6, v254, 48
	s_add_i32 s9, s9, s6
	v_and_b32_e32 v34, 15, v136
	v_or_b32_e32 v146, s9, v34
	v_ashrrev_i32_e32 v147, 31, v146
	v_lshlrev_b64 v[138:139], 5, v[146:147]
	v_lshl_add_u64 v[144:145], s[18:19], 0, v[138:139]
	global_load_dwordx4 v[138:141], v[144:145], off
	global_load_dwordx4 v[156:159], v[144:145], off offset:16
	s_mov_b32 s100, 0x1000
	s_mov_b32 s101, 0
	v_lshl_add_u64 v[250:251], v[144:145], 0, s[100:101]
	global_load_dwordx4 v[172:175], v[144:145], off offset:512
	global_load_dwordx4 v[176:179], v[144:145], off offset:528
	global_load_dwordx4 v[180:183], v[144:145], off offset:1024
	global_load_dwordx4 v[184:187], v[144:145], off offset:1040
	global_load_dwordx4 v[188:191], v[144:145], off offset:1536
	global_load_dwordx4 v[192:195], v[144:145], off offset:1552
	global_load_dwordx4 v[196:199], v[250:251], off
	global_load_dwordx4 v[200:203], v[250:251], off offset:16
	global_load_dwordx4 v[204:207], v[250:251], off offset:512
	global_load_dwordx4 v[208:211], v[250:251], off offset:528
	global_load_dwordx4 v[224:227], v[250:251], off offset:1024
	global_load_dwordx4 v[228:231], v[250:251], off offset:1040
	global_load_dwordx4 v[232:235], v[250:251], off offset:1536
	global_load_dwordx4 v[236:239], v[250:251], off offset:1552
	s_lshl_b32 s88, s7, 7
	v_bfe_u32 v155, v136, 4, 2
	v_lshl_or_b32 v136, v155, 3, s88
	v_or_b32_e32 v136, s26, v136
	v_ashrrev_i32_e32 v137, 31, v136
	v_lshlrev_b64 v[136:137], 14, v[136:137]
	v_or_b32_e32 v148, 16, v146
	v_ashrrev_i32_e32 v149, 31, v148
	v_lshlrev_b64 v[148:149], 5, v[148:149]
	v_lshl_add_u64 v[148:149], s[18:19], 0, v[148:149]
	v_permlane32_swap_b32_e32 v2, v18
	v_permlane32_swap_b32_e32 v3, v19
	v_permlane32_swap_b32_e32 v10, v26
	v_permlane32_swap_b32_e32 v11, v27
	v_permlane32_swap_b32_e32 v4, v20
	v_permlane32_swap_b32_e32 v5, v21
	v_permlane32_swap_b32_e32 v6, v22
	v_permlane32_swap_b32_e32 v7, v23
	v_permlane32_swap_b32_e32 v8, v24
	v_permlane32_swap_b32_e32 v9, v25
	v_permlane32_swap_b32_e32 v12, v28
	v_permlane32_swap_b32_e32 v13, v29
	v_permlane32_swap_b32_e32 v14, v30
	v_permlane32_swap_b32_e32 v15, v31
	v_permlane32_swap_b32_e32 v16, v32
	v_permlane32_swap_b32_e32 v17, v33
	v_permlane16_swap_b32_e32 v2, v10
	v_permlane16_swap_b32_e32 v3, v11
	v_permlane16_swap_b32_e32 v18, v26
	v_permlane16_swap_b32_e32 v19, v27
	v_permlane16_swap_b32_e32 v4, v12
	v_permlane16_swap_b32_e32 v5, v13
	v_permlane16_swap_b32_e32 v6, v14
	v_permlane16_swap_b32_e32 v7, v15
	v_permlane16_swap_b32_e32 v8, v16
	v_permlane16_swap_b32_e32 v9, v17
	v_permlane16_swap_b32_e32 v20, v28
	v_permlane16_swap_b32_e32 v21, v29
	v_permlane16_swap_b32_e32 v22, v30
	v_permlane16_swap_b32_e32 v23, v31
	v_permlane16_swap_b32_e32 v24, v32
	v_permlane16_swap_b32_e32 v25, v33
	s_ashr_i32 s89, s88, 31
	v_permlane32_swap_b32_e32 v36, v40
	v_permlane32_swap_b32_e32 v37, v41
	s_waitcnt vmcnt(14)
	v_pk_add_f32 v[140:141], v[140:141], v[158:159]
	v_pk_add_f32 v[138:139], v[138:139], v[156:157]
	v_permlane32_swap_b32_e32 v38, v42
	v_pk_mov_b32 v[142:143], v[138:139], v[140:141] op_sel:[1,0]
	v_mov_b32_e32 v139, v141
	v_pk_add_f32 v[138:139], v[142:143], v[138:139]
	v_permlane32_swap_b32_e32 v39, v43
	v_add_f32_e32 v138, v138, v139
	v_fmamk_f32 v138, v138, 0x3b800000, v153
	v_cmp_gt_f32_e32 vcc, s16, v138
	v_mul_f32_e32 v139, 0x4f800000, v138
	v_permlane32_swap_b32_e32 v44, v48
	v_cndmask_b32_e32 v138, v138, v139, vcc
	v_sqrt_f32_e32 v139, v138
	v_permlane32_swap_b32_e32 v45, v49
	v_permlane32_swap_b32_e32 v46, v50
	v_add_u32_e32 v140, -1, v139
	v_fma_f32 v141, -v140, v139, v138
	v_cmp_ge_f32_e64 s[6:7], 0, v141
	v_add_u32_e32 v141, 1, v139
	v_permlane32_swap_b32_e32 v47, v51
	v_cndmask_b32_e64 v140, v139, v140, s[6:7]
	v_fma_f32 v139, -v141, v139, v138
	v_cmp_lt_f32_e64 s[6:7], 0, v139
	v_permlane32_swap_b32_e32 v52, v56
	s_nop 0
	v_cndmask_b32_e64 v139, v140, v141, s[6:7]
	v_mul_f32_e32 v140, 0x37800000, v139
	v_cndmask_b32_e32 v139, v139, v140, vcc
	v_cmp_class_f32_e32 vcc, v138, v154
	v_permlane32_swap_b32_e32 v53, v57
	s_nop 0
	v_cndmask_b32_e32 v138, v139, v138, vcc
	v_div_scale_f32 v139, s[6:7], v138, v138, 1.0
	v_rcp_f32_e32 v140, v139
	s_mov_b32 s6, 0x10000
	v_permlane32_swap_b32_e32 v54, v58
	v_fma_f32 v141, -v139, v140, 1.0
	v_fmac_f32_e32 v140, v141, v140
	v_div_scale_f32 v141, vcc, 1.0, v138, 1.0
	v_mul_f32_e32 v142, v141, v140
	v_fma_f32 v143, -v139, v142, v141
	v_fmac_f32_e32 v142, v143, v140
	v_fma_f32 v139, -v139, v142, v141
	v_div_fmas_f32 v139, v139, v140, v142
	v_div_fixup_f32 v138, v139, v138, 1.0
	v_pk_mul_f32 v[124:125], v[124:125], v[138:139] op_sel_hi:[1,0]
	v_mov_b32_e32 v140, 0
	v_cvt_pk_fp8_f32 v140, v124, v125
	v_pk_mul_f32 v[128:129], v[128:129], v[138:139] op_sel_hi:[1,0]
	v_mov_b32_e32 v142, 0
	v_cvt_pk_fp8_f32 v142, v128, v129
	v_pk_mul_f32 v[126:127], v[126:127], v[138:139] op_sel_hi:[1,0]
	v_lshl_add_u64 v[124:125], s[20:21], 0, v[136:137]
	v_cvt_pk_fp8_f32 v140, v126, v127 op_sel:[0,0,1]
	v_lshl_add_u64 v[124:125], v[124:125], 0, v[146:147]
	v_pk_mul_f32 v[130:131], v[130:131], v[138:139] op_sel_hi:[1,0]
	v_add_co_u32_e32 v126, vcc, s6, v124
	v_cvt_pk_fp8_f32 v142, v130, v131 op_sel:[0,0,1]
	s_nop 0
	v_addc_co_u32_e32 v127, vcc, 0, v125, vcc
	s_movk_i32 s6, 0x4000
	v_add_co_u32_e32 v128, vcc, s6, v124
	v_lshrrev_b32_e32 v130, 8, v140
	s_nop 0
	v_addc_co_u32_e32 v129, vcc, 0, v125, vcc
	s_mov_b32 s6, 0x14000
	global_store_byte v[128:129], v130, off
	v_add_co_u32_e32 v130, vcc, s6, v124
	v_lshrrev_b32_e32 v136, 8, v142
	s_nop 0
	v_addc_co_u32_e32 v131, vcc, 0, v125, vcc
	s_mov_b32 s6, 0x8000
	global_store_byte v[130:131], v136, off
	v_add_co_u32_e32 v136, vcc, s6, v124
	s_mov_b32 s6, 0x18000
	s_nop 0
	v_addc_co_u32_e32 v137, vcc, 0, v125, vcc
	v_add_co_u32_e32 v138, vcc, s6, v124
	s_mov_b32 s6, 0xc000
	s_nop 0
	v_addc_co_u32_e32 v139, vcc, 0, v125, vcc
	global_store_byte v[124:125], v140, off
	global_store_byte_d16_hi v[136:137], v140, off
	v_lshrrev_b32_e32 v143, 24, v140
	v_add_co_u32_e32 v140, vcc, s6, v124
	s_mov_b32 s6, 0x1c000
	s_nop 0
	v_addc_co_u32_e32 v141, vcc, 0, v125, vcc
	global_store_byte v[126:127], v142, off
	global_store_byte_d16_hi v[138:139], v142, off
	v_lshrrev_b32_e32 v147, 24, v142
	v_add_co_u32_e32 v142, vcc, s6, v124
	global_store_byte v[140:141], v143, off
	s_nop 0
	v_addc_co_u32_e32 v143, vcc, 0, v125, vcc
	global_store_byte v[142:143], v147, off
	v_permlane32_swap_b32_e32 v55, v59
	v_permlane32_swap_b32_e32 v60, v64
	v_permlane32_swap_b32_e32 v61, v65
	v_permlane32_swap_b32_e32 v62, v66
	v_permlane32_swap_b32_e32 v63, v67
	v_permlane16_swap_b32_e32 v36, v52
	v_permlane16_swap_b32_e32 v37, v53
	v_permlane16_swap_b32_e32 v38, v54
	v_permlane16_swap_b32_e32 v39, v55
	v_permlane16_swap_b32_e32 v44, v60
	v_permlane16_swap_b32_e32 v45, v61
	v_permlane16_swap_b32_e32 v46, v62
	v_permlane16_swap_b32_e32 v47, v63
	v_permlane16_swap_b32_e32 v40, v56
	v_permlane16_swap_b32_e32 v41, v57
	v_permlane16_swap_b32_e32 v42, v58
	v_permlane16_swap_b32_e32 v43, v59
	v_permlane16_swap_b32_e32 v48, v64
	v_permlane16_swap_b32_e32 v49, v65
	v_permlane16_swap_b32_e32 v50, v66
	v_permlane16_swap_b32_e32 v51, v67
	s_cmp_eq_u32 s0, s50
	s_waitcnt vmcnt(20)
	v_pk_add_f32 v[148:149], v[174:175], v[178:179]
	v_pk_add_f32 v[156:157], v[172:173], v[176:177]
	s_nop 0
	v_pk_mov_b32 v[158:159], v[156:157], v[148:149] op_sel:[1,0]
	v_mov_b32_e32 v157, v149
	v_pk_add_f32 v[148:149], v[158:159], v[156:157]
	s_nop 0
	v_add_f32_e32 v147, v148, v149
	v_fmamk_f32 v147, v147, 0x3b800000, v153
	v_cmp_gt_f32_e32 vcc, s16, v147
	v_mul_f32_e32 v148, 0x4f800000, v147
	s_nop 0
	v_cndmask_b32_e32 v147, v147, v148, vcc
	v_sqrt_f32_e32 v148, v147
	s_nop 0
	v_add_u32_e32 v149, -1, v148
	v_fma_f32 v156, -v149, v148, v147
	v_cmp_ge_f32_e64 s[6:7], 0, v156
	v_add_u32_e32 v156, 1, v148
	s_nop 0
	v_cndmask_b32_e64 v149, v148, v149, s[6:7]
	v_fma_f32 v148, -v156, v148, v147
	v_cmp_lt_f32_e64 s[6:7], 0, v148
	s_nop 1
	v_cndmask_b32_e64 v148, v149, v156, s[6:7]
	v_mul_f32_e32 v149, 0x37800000, v148
	v_cndmask_b32_e32 v148, v148, v149, vcc
	v_cmp_class_f32_e32 vcc, v147, v154
	s_nop 1
	v_cndmask_b32_e32 v147, v148, v147, vcc
	v_div_scale_f32 v148, s[6:7], v147, v147, 1.0
	v_rcp_f32_e32 v149, v148
	s_nop 0
	v_fma_f32 v156, -v148, v149, 1.0
	v_fmac_f32_e32 v149, v156, v149
	v_div_scale_f32 v156, vcc, 1.0, v147, 1.0
	v_mul_f32_e32 v157, v156, v149
	v_fma_f32 v158, -v148, v157, v156
	v_fmac_f32_e32 v157, v158, v149
	v_fma_f32 v148, -v148, v157, v156
	v_div_fmas_f32 v148, v148, v149, v157
	v_div_fixup_f32 v148, v148, v147, 1.0
	v_pk_mul_f32 v[116:117], v[116:117], v[148:149] op_sel_hi:[1,0]
	v_mov_b32_e32 v147, 0
	v_pk_mul_f32 v[120:121], v[120:121], v[148:149] op_sel_hi:[1,0]
	v_cvt_pk_fp8_f32 v147, v116, v117
	v_mov_b32_e32 v116, 0
	v_cvt_pk_fp8_f32 v116, v120, v121
	v_pk_mul_f32 v[118:119], v[118:119], v[148:149] op_sel_hi:[1,0]
	v_pk_mul_f32 v[122:123], v[122:123], v[148:149] op_sel_hi:[1,0]
	v_cvt_pk_fp8_f32 v147, v118, v119 op_sel:[0,0,1]
	v_cvt_pk_fp8_f32 v116, v122, v123 op_sel:[0,0,1]
	global_store_byte v[124:125], v147, off offset:16
	global_store_byte v[126:127], v116, off offset:16
	v_lshrrev_b32_e32 v117, 8, v147
	global_store_byte v[128:129], v117, off offset:16
	v_lshrrev_b32_e32 v117, 8, v116
	global_store_byte v[130:131], v117, off offset:16
	global_store_byte_d16_hi v[136:137], v147, off offset:16
	global_store_byte_d16_hi v[138:139], v116, off offset:16
	v_lshrrev_b32_e32 v116, 24, v116
	v_lshrrev_b32_e32 v117, 24, v147
	global_store_byte v[142:143], v116, off offset:16
	v_or_b32_e32 v116, 32, v146
	global_store_byte v[140:141], v117, off offset:16
	v_ashrrev_i32_e32 v117, 31, v116
	v_lshlrev_b64 v[116:117], 5, v[116:117]
	v_lshl_add_u64 v[120:121], s[18:19], 0, v[116:117]
	s_nop 0
	s_waitcnt vmcnt(26)
	v_pk_add_f32 v[118:119], v[182:183], v[186:187]
	v_pk_add_f32 v[116:117], v[180:181], v[184:185]
	s_nop 0
	v_pk_mov_b32 v[120:121], v[116:117], v[118:119] op_sel:[1,0]
	v_mov_b32_e32 v117, v119
	v_pk_add_f32 v[116:117], v[120:121], v[116:117]
	s_nop 0
	v_add_f32_e32 v116, v116, v117
	v_fmamk_f32 v116, v116, 0x3b800000, v153
	v_cmp_gt_f32_e32 vcc, s16, v116
	v_mul_f32_e32 v117, 0x4f800000, v116
	s_nop 0
	v_cndmask_b32_e32 v116, v116, v117, vcc
	v_sqrt_f32_e32 v117, v116
	s_nop 0
	v_add_u32_e32 v118, -1, v117
	v_fma_f32 v119, -v118, v117, v116
	v_cmp_ge_f32_e64 s[6:7], 0, v119
	v_add_u32_e32 v119, 1, v117
	s_nop 0
	v_cndmask_b32_e64 v118, v117, v118, s[6:7]
	v_fma_f32 v117, -v119, v117, v116
	v_cmp_lt_f32_e64 s[6:7], 0, v117
	s_nop 1
	v_cndmask_b32_e64 v117, v118, v119, s[6:7]
	v_mul_f32_e32 v118, 0x37800000, v117
	v_cndmask_b32_e32 v117, v117, v118, vcc
	v_cmp_class_f32_e32 vcc, v116, v154
	s_nop 1
	v_cndmask_b32_e32 v116, v117, v116, vcc
	v_div_scale_f32 v117, s[6:7], v116, v116, 1.0
	v_rcp_f32_e32 v118, v117
	s_nop 0
	v_fma_f32 v119, -v117, v118, 1.0
	v_fmac_f32_e32 v118, v119, v118
	v_div_scale_f32 v119, vcc, 1.0, v116, 1.0
	v_mul_f32_e32 v120, v119, v118
	v_fma_f32 v121, -v117, v120, v119
	v_fmac_f32_e32 v120, v121, v118
	v_fma_f32 v117, -v117, v120, v119
	v_div_fmas_f32 v117, v117, v118, v120
	v_div_fixup_f32 v116, v117, v116, 1.0
	v_pk_mul_f32 v[110:111], v[110:111], v[116:117] op_sel_hi:[1,0]
	v_pk_mul_f32 v[108:109], v[108:109], v[116:117] op_sel_hi:[1,0]
	v_pk_mul_f32 v[114:115], v[114:115], v[116:117] op_sel_hi:[1,0]
	v_pk_mul_f32 v[112:113], v[112:113], v[116:117] op_sel_hi:[1,0]
	v_mov_b32_e32 v116, 0
	v_cvt_pk_fp8_f32 v116, v108, v109
	v_mov_b32_e32 v108, 0
	v_cvt_pk_fp8_f32 v108, v112, v113
	v_cvt_pk_fp8_f32 v116, v110, v111 op_sel:[0,0,1]
	v_cvt_pk_fp8_f32 v108, v114, v115 op_sel:[0,0,1]
	global_store_byte v[124:125], v116, off offset:32
	global_store_byte v[126:127], v108, off offset:32
	v_lshrrev_b32_e32 v109, 8, v116
	global_store_byte v[128:129], v109, off offset:32
	v_lshrrev_b32_e32 v109, 8, v108
	global_store_byte v[130:131], v109, off offset:32
	global_store_byte_d16_hi v[136:137], v116, off offset:32
	global_store_byte_d16_hi v[138:139], v108, off offset:32
	v_lshrrev_b32_e32 v108, 24, v108
	v_lshrrev_b32_e32 v109, 24, v116
	global_store_byte v[142:143], v108, off offset:32
	v_or_b32_e32 v108, 48, v146
	global_store_byte v[140:141], v109, off offset:32
	v_ashrrev_i32_e32 v109, 31, v108
	v_lshlrev_b64 v[108:109], 5, v[108:109]
	v_lshl_add_u64 v[112:113], s[18:19], 0, v[108:109]
	s_nop 0
	s_waitcnt vmcnt(32)
	v_pk_add_f32 v[110:111], v[190:191], v[194:195]
	v_pk_add_f32 v[108:109], v[188:189], v[192:193]
	s_nop 0
	v_pk_mov_b32 v[112:113], v[108:109], v[110:111] op_sel:[1,0]
	v_mov_b32_e32 v109, v111
	v_pk_add_f32 v[108:109], v[112:113], v[108:109]
	s_nop 0
	v_add_f32_e32 v108, v108, v109
	v_fmamk_f32 v108, v108, 0x3b800000, v153
	v_cmp_gt_f32_e32 vcc, s16, v108
	v_mul_f32_e32 v109, 0x4f800000, v108
	s_nop 0
	v_cndmask_b32_e32 v108, v108, v109, vcc
	v_sqrt_f32_e32 v109, v108
	s_nop 0
	v_add_u32_e32 v110, -1, v109
	v_fma_f32 v111, -v110, v109, v108
	v_cmp_ge_f32_e64 s[6:7], 0, v111
	v_add_u32_e32 v111, 1, v109
	s_nop 0
	v_cndmask_b32_e64 v110, v109, v110, s[6:7]
	v_fma_f32 v109, -v111, v109, v108
	v_cmp_lt_f32_e64 s[6:7], 0, v109
	s_nop 1
	v_cndmask_b32_e64 v109, v110, v111, s[6:7]
	v_mul_f32_e32 v110, 0x37800000, v109
	v_cndmask_b32_e32 v109, v109, v110, vcc
	v_cmp_class_f32_e32 vcc, v108, v154
	s_nop 1
	v_cndmask_b32_e32 v108, v109, v108, vcc
	v_div_scale_f32 v109, s[6:7], v108, v108, 1.0
	v_rcp_f32_e32 v110, v109
	s_mov_b64 s[6:7], 0x1000
	v_fma_f32 v111, -v109, v110, 1.0
	v_fmac_f32_e32 v110, v111, v110
	v_div_scale_f32 v111, vcc, 1.0, v108, 1.0
	v_mul_f32_e32 v112, v111, v110
	v_fma_f32 v113, -v109, v112, v111
	v_fmac_f32_e32 v112, v113, v110
	v_fma_f32 v109, -v109, v112, v111
	v_div_fmas_f32 v109, v109, v110, v112
	v_div_fixup_f32 v108, v109, v108, 1.0
	v_pk_mul_f32 v[102:103], v[102:103], v[108:109] op_sel_hi:[1,0]
	v_pk_mul_f32 v[100:101], v[100:101], v[108:109] op_sel_hi:[1,0]
	v_pk_mul_f32 v[106:107], v[106:107], v[108:109] op_sel_hi:[1,0]
	v_pk_mul_f32 v[104:105], v[104:105], v[108:109] op_sel_hi:[1,0]
	v_mov_b32_e32 v108, 0
	v_cvt_pk_fp8_f32 v108, v100, v101
	v_mov_b32_e32 v100, 0
	v_cvt_pk_fp8_f32 v100, v104, v105
	v_cvt_pk_fp8_f32 v108, v102, v103 op_sel:[0,0,1]
	v_cvt_pk_fp8_f32 v100, v106, v107 op_sel:[0,0,1]
	global_store_byte v[124:125], v108, off offset:48
	global_store_byte v[126:127], v100, off offset:48
	v_lshrrev_b32_e32 v101, 8, v108
	global_store_byte v[128:129], v101, off offset:48
	v_lshrrev_b32_e32 v101, 8, v100
	global_store_byte v[130:131], v101, off offset:48
	global_store_byte_d16_hi v[136:137], v108, off offset:48
	global_store_byte_d16_hi v[138:139], v100, off offset:48
	v_lshrrev_b32_e32 v100, 24, v100
	v_lshl_add_u64 v[106:107], v[144:145], 0, s[6:7]
	s_movk_i32 s6, 0x1000
	v_lshrrev_b32_e32 v101, 24, v108
	global_store_byte v[142:143], v100, off offset:48
	v_add_co_u32_e32 v100, vcc, s6, v144
	global_store_byte v[140:141], v101, off offset:48
	s_nop 0
	v_addc_co_u32_e32 v101, vcc, 0, v145, vcc
	s_nop 0
	s_waitcnt vmcnt(38)
	v_pk_add_f32 v[104:105], v[198:199], v[202:203]
	v_pk_add_f32 v[102:103], v[196:197], v[200:201]
	s_nop 0
	v_pk_mov_b32 v[106:107], v[102:103], v[104:105] op_sel:[1,0]
	v_mov_b32_e32 v103, v105
	v_pk_add_f32 v[102:103], v[106:107], v[102:103]
	s_nop 0
	v_add_f32_e32 v102, v102, v103
	v_fmamk_f32 v102, v102, 0x3b800000, v153
	v_cmp_gt_f32_e32 vcc, s16, v102
	v_mul_f32_e32 v103, 0x4f800000, v102
	s_nop 0
	v_cndmask_b32_e32 v102, v102, v103, vcc
	v_sqrt_f32_e32 v103, v102
	s_nop 0
	v_add_u32_e32 v104, -1, v103
	v_fma_f32 v105, -v104, v103, v102
	v_cmp_ge_f32_e64 s[6:7], 0, v105
	v_add_u32_e32 v105, 1, v103
	s_nop 0
	v_cndmask_b32_e64 v104, v103, v104, s[6:7]
	v_fma_f32 v103, -v105, v103, v102
	v_cmp_lt_f32_e64 s[6:7], 0, v103
	s_nop 1
	v_cndmask_b32_e64 v103, v104, v105, s[6:7]
	v_mul_f32_e32 v104, 0x37800000, v103
	v_cndmask_b32_e32 v103, v103, v104, vcc
	v_cmp_class_f32_e32 vcc, v102, v154
	s_nop 1
	v_cndmask_b32_e32 v102, v103, v102, vcc
	v_div_scale_f32 v103, s[6:7], v102, v102, 1.0
	v_rcp_f32_e32 v104, v103
	s_mov_b64 s[6:7], 0x1200
	v_fma_f32 v105, -v103, v104, 1.0
	v_fmac_f32_e32 v104, v105, v104
	v_div_scale_f32 v105, vcc, 1.0, v102, 1.0
	v_mul_f32_e32 v106, v105, v104
	v_fma_f32 v107, -v103, v106, v105
	v_fmac_f32_e32 v106, v107, v104
	v_fma_f32 v103, -v103, v106, v105
	v_div_fmas_f32 v103, v103, v104, v106
	v_div_fixup_f32 v102, v103, v102, 1.0
	v_pk_mul_f32 v[104:105], v[92:93], v[102:103] op_sel_hi:[1,0]
	v_pk_mul_f32 v[92:93], v[98:99], v[102:103] op_sel_hi:[1,0]
	v_mov_b32_e32 v98, 0
	v_cvt_pk_fp8_f32 v98, v104, v105
	v_pk_mul_f32 v[94:95], v[94:95], v[102:103] op_sel_hi:[1,0]
	v_pk_mul_f32 v[96:97], v[96:97], v[102:103] op_sel_hi:[1,0]
	v_cvt_pk_fp8_f32 v98, v94, v95 op_sel:[0,0,1]
	v_mov_b32_e32 v94, 0
	v_cvt_pk_fp8_f32 v94, v96, v97
	v_lshl_add_u64 v[96:97], v[144:145], 0, s[6:7]
	v_cvt_pk_fp8_f32 v94, v92, v93 op_sel:[0,0,1]
	v_lshrrev_b32_e32 v92, 8, v98
	global_store_byte v[124:125], v98, off offset:128
	global_store_byte v[126:127], v94, off offset:128
	global_store_byte v[128:129], v92, off offset:128
	v_lshrrev_b32_e32 v92, 8, v94
	global_store_byte v[130:131], v92, off offset:128
	global_store_byte_d16_hi v[136:137], v98, off offset:128
	global_store_byte_d16_hi v[138:139], v94, off offset:128
	v_lshrrev_b32_e32 v92, 24, v98
	global_store_byte v[140:141], v92, off offset:128
	v_lshrrev_b32_e32 v92, 24, v94
	global_store_byte v[142:143], v92, off offset:128
	s_nop 0
	s_waitcnt vmcnt(44)
	v_pk_add_f32 v[94:95], v[206:207], v[210:211]
	v_pk_add_f32 v[92:93], v[204:205], v[208:209]
	s_nop 0
	v_pk_mov_b32 v[96:97], v[92:93], v[94:95] op_sel:[1,0]
	v_mov_b32_e32 v93, v95
	v_pk_add_f32 v[92:93], v[96:97], v[92:93]
	s_nop 0
	v_add_f32_e32 v92, v92, v93
	v_fmamk_f32 v92, v92, 0x3b800000, v153
	v_cmp_gt_f32_e32 vcc, s16, v92
	v_mul_f32_e32 v93, 0x4f800000, v92
	s_nop 0
	v_cndmask_b32_e32 v92, v92, v93, vcc
	v_sqrt_f32_e32 v93, v92
	s_nop 0
	v_add_u32_e32 v94, -1, v93
	v_fma_f32 v95, -v94, v93, v92
	v_cmp_ge_f32_e64 s[6:7], 0, v95
	v_add_u32_e32 v95, 1, v93
	s_nop 0
	v_cndmask_b32_e64 v94, v93, v94, s[6:7]
	v_fma_f32 v93, -v95, v93, v92
	v_cmp_lt_f32_e64 s[6:7], 0, v93
	s_nop 1
	v_cndmask_b32_e64 v93, v94, v95, s[6:7]
	v_mul_f32_e32 v94, 0x37800000, v93
	v_cndmask_b32_e32 v93, v93, v94, vcc
	v_cmp_class_f32_e32 vcc, v92, v154
	s_nop 1
	v_cndmask_b32_e32 v92, v93, v92, vcc
	v_div_scale_f32 v93, s[6:7], v92, v92, 1.0
	v_rcp_f32_e32 v94, v93
	s_mov_b64 s[6:7], 0x1400
	v_fma_f32 v95, -v93, v94, 1.0
	v_fmac_f32_e32 v94, v95, v94
	v_div_scale_f32 v95, vcc, 1.0, v92, 1.0
	v_mul_f32_e32 v96, v95, v94
	v_fma_f32 v97, -v93, v96, v95
	v_fmac_f32_e32 v96, v97, v94
	v_fma_f32 v93, -v93, v96, v95
	v_div_fmas_f32 v93, v93, v94, v96
	v_div_fixup_f32 v92, v93, v92, 1.0
	v_pk_mul_f32 v[94:95], v[84:85], v[92:93] op_sel_hi:[1,0]
	v_pk_mul_f32 v[84:85], v[90:91], v[92:93] op_sel_hi:[1,0]
	v_mov_b32_e32 v90, 0
	v_cvt_pk_fp8_f32 v90, v94, v95
	v_pk_mul_f32 v[86:87], v[86:87], v[92:93] op_sel_hi:[1,0]
	v_pk_mul_f32 v[88:89], v[88:89], v[92:93] op_sel_hi:[1,0]
	v_cvt_pk_fp8_f32 v90, v86, v87 op_sel:[0,0,1]
	v_mov_b32_e32 v86, 0
	v_cvt_pk_fp8_f32 v86, v88, v89
	v_lshl_add_u64 v[88:89], v[144:145], 0, s[6:7]
	v_cvt_pk_fp8_f32 v86, v84, v85 op_sel:[0,0,1]
	v_lshrrev_b32_e32 v84, 8, v90
	global_store_byte v[124:125], v90, off offset:144
	global_store_byte v[126:127], v86, off offset:144
	global_store_byte v[128:129], v84, off offset:144
	v_lshrrev_b32_e32 v84, 8, v86
	global_store_byte v[130:131], v84, off offset:144
	global_store_byte_d16_hi v[136:137], v90, off offset:144
	global_store_byte_d16_hi v[138:139], v86, off offset:144
	v_lshrrev_b32_e32 v84, 24, v90
	global_store_byte v[140:141], v84, off offset:144
	v_lshrrev_b32_e32 v84, 24, v86
	global_store_byte v[142:143], v84, off offset:144
	s_nop 0
	s_waitcnt vmcnt(50)
	v_pk_add_f32 v[86:87], v[226:227], v[230:231]
	v_pk_add_f32 v[84:85], v[224:225], v[228:229]
	s_nop 0
	v_pk_mov_b32 v[88:89], v[84:85], v[86:87] op_sel:[1,0]
	v_mov_b32_e32 v85, v87
	v_pk_add_f32 v[84:85], v[88:89], v[84:85]
	s_nop 0
	v_add_f32_e32 v84, v84, v85
	v_fmamk_f32 v84, v84, 0x3b800000, v153
	v_cmp_gt_f32_e32 vcc, s16, v84
	v_mul_f32_e32 v85, 0x4f800000, v84
	s_nop 0
	v_cndmask_b32_e32 v84, v84, v85, vcc
	v_sqrt_f32_e32 v85, v84
	s_nop 0
	v_add_u32_e32 v86, -1, v85
	v_fma_f32 v87, -v86, v85, v84
	v_cmp_ge_f32_e64 s[6:7], 0, v87
	v_add_u32_e32 v87, 1, v85
	s_nop 0
	v_cndmask_b32_e64 v86, v85, v86, s[6:7]
	v_fma_f32 v85, -v87, v85, v84
	v_cmp_lt_f32_e64 s[6:7], 0, v85
	s_nop 1
	v_cndmask_b32_e64 v85, v86, v87, s[6:7]
	v_mul_f32_e32 v86, 0x37800000, v85
	v_cndmask_b32_e32 v85, v85, v86, vcc
	v_cmp_class_f32_e32 vcc, v84, v154
	s_nop 1
	v_cndmask_b32_e32 v84, v85, v84, vcc
	v_div_scale_f32 v85, s[6:7], v84, v84, 1.0
	v_rcp_f32_e32 v86, v85
	s_mov_b64 s[6:7], 0x1600
	v_fma_f32 v87, -v85, v86, 1.0
	v_fmac_f32_e32 v86, v87, v86
	v_div_scale_f32 v87, vcc, 1.0, v84, 1.0
	v_mul_f32_e32 v88, v87, v86
	v_fma_f32 v89, -v85, v88, v87
	v_fmac_f32_e32 v88, v89, v86
	v_fma_f32 v85, -v85, v88, v87
	v_div_fmas_f32 v85, v85, v86, v88
	v_div_fixup_f32 v84, v85, v84, 1.0
	v_pk_mul_f32 v[86:87], v[76:77], v[84:85] op_sel_hi:[1,0]
	v_pk_mul_f32 v[76:77], v[82:83], v[84:85] op_sel_hi:[1,0]
	v_mov_b32_e32 v82, 0
	v_cvt_pk_fp8_f32 v82, v86, v87
	v_pk_mul_f32 v[78:79], v[78:79], v[84:85] op_sel_hi:[1,0]
	v_pk_mul_f32 v[80:81], v[80:81], v[84:85] op_sel_hi:[1,0]
	v_cvt_pk_fp8_f32 v82, v78, v79 op_sel:[0,0,1]
	v_mov_b32_e32 v78, 0
	v_cvt_pk_fp8_f32 v78, v80, v81
	v_lshl_add_u64 v[80:81], v[144:145], 0, s[6:7]
	v_cvt_pk_fp8_f32 v78, v76, v77 op_sel:[0,0,1]
	v_lshrrev_b32_e32 v76, 8, v82
	global_store_byte v[124:125], v82, off offset:160
	global_store_byte v[126:127], v78, off offset:160
	global_store_byte v[128:129], v76, off offset:160
	v_lshrrev_b32_e32 v76, 8, v78
	global_store_byte v[130:131], v76, off offset:160
	global_store_byte_d16_hi v[136:137], v82, off offset:160
	global_store_byte_d16_hi v[138:139], v78, off offset:160
	v_lshrrev_b32_e32 v76, 24, v82
	global_store_byte v[140:141], v76, off offset:160
	v_lshrrev_b32_e32 v76, 24, v78
	global_store_byte v[142:143], v76, off offset:160
	s_nop 0
	s_waitcnt vmcnt(56)
	v_pk_add_f32 v[78:79], v[234:235], v[238:239]
	v_pk_add_f32 v[76:77], v[232:233], v[236:237]
	s_nop 0
	v_pk_mov_b32 v[80:81], v[76:77], v[78:79] op_sel:[1,0]
	v_mov_b32_e32 v77, v79
	v_pk_add_f32 v[76:77], v[80:81], v[76:77]
	s_nop 0
	v_add_f32_e32 v76, v76, v77
	v_fmamk_f32 v76, v76, 0x3b800000, v153
	v_cmp_gt_f32_e32 vcc, s16, v76
	v_mul_f32_e32 v77, 0x4f800000, v76
	s_nop 0
	v_cndmask_b32_e32 v76, v76, v77, vcc
	v_sqrt_f32_e32 v77, v76
	s_nop 0
	v_add_u32_e32 v78, -1, v77
	v_fma_f32 v79, -v78, v77, v76
	v_cmp_ge_f32_e64 s[6:7], 0, v79
	v_add_u32_e32 v79, 1, v77
	s_nop 0
	v_cndmask_b32_e64 v78, v77, v78, s[6:7]
	v_fma_f32 v77, -v79, v77, v76
	v_cmp_lt_f32_e64 s[6:7], 0, v77
	s_nop 1
	v_cndmask_b32_e64 v77, v78, v79, s[6:7]
	v_mul_f32_e32 v78, 0x37800000, v77
	v_cndmask_b32_e32 v77, v77, v78, vcc
	v_cmp_class_f32_e32 vcc, v76, v154
	s_nop 1
	v_cndmask_b32_e32 v76, v77, v76, vcc
	v_div_scale_f32 v77, s[6:7], v76, v76, 1.0
	v_rcp_f32_e32 v78, v77
	s_nop 0
	v_fma_f32 v79, -v77, v78, 1.0
	v_fmac_f32_e32 v78, v79, v78
	v_div_scale_f32 v79, vcc, 1.0, v76, 1.0
	v_mul_f32_e32 v80, v79, v78
	v_fma_f32 v81, -v77, v80, v79
	v_fmac_f32_e32 v80, v81, v78
	v_fma_f32 v77, -v77, v80, v79
	v_div_fmas_f32 v77, v77, v78, v80
	v_div_fixup_f32 v76, v77, v76, 1.0
	v_pk_mul_f32 v[70:71], v[70:71], v[76:77] op_sel_hi:[1,0]
	v_pk_mul_f32 v[68:69], v[68:69], v[76:77] op_sel_hi:[1,0]
	v_pk_mul_f32 v[74:75], v[74:75], v[76:77] op_sel_hi:[1,0]
	v_pk_mul_f32 v[72:73], v[72:73], v[76:77] op_sel_hi:[1,0]
	v_mov_b32_e32 v76, 0
	v_cvt_pk_fp8_f32 v76, v68, v69
	v_mov_b32_e32 v68, 0
	v_cvt_pk_fp8_f32 v68, v72, v73
	v_cvt_pk_fp8_f32 v76, v70, v71 op_sel:[0,0,1]
	v_cvt_pk_fp8_f32 v68, v74, v75 op_sel:[0,0,1]
	global_store_byte v[124:125], v76, off offset:176
	global_store_byte v[126:127], v68, off offset:176
	v_lshrrev_b32_e32 v69, 8, v76
	global_store_byte v[128:129], v69, off offset:176
	v_lshrrev_b32_e32 v69, 8, v68
	global_store_byte v[130:131], v69, off offset:176
	global_store_byte_d16_hi v[136:137], v76, off offset:176
	global_store_byte_d16_hi v[138:139], v68, off offset:176
	v_lshrrev_b32_e32 v68, 24, v68
	global_store_byte v[142:143], v68, off offset:176
	v_lshlrev_b32_e32 v68, 4, v155
	v_lshrrev_b32_e32 v69, 24, v76
	v_or3_b32 v68, v68, s9, v34
	global_store_byte v[140:141], v69, off offset:176
	v_ashrrev_i32_e32 v69, 31, v68
	v_lshlrev_b64 v[70:71], 5, v[68:69]
	v_lshl_add_u64 v[74:75], s[18:19], 0, v[70:71]
	global_load_dwordx4 v[70:73], v[74:75], off
	s_nop 0
	global_load_dwordx4 v[74:77], v[74:75], off offset:16
	s_waitcnt vmcnt(0)
	v_pk_add_f32 v[72:73], v[72:73], v[76:77]
	v_pk_add_f32 v[70:71], v[70:71], v[74:75]
	s_nop 0
	v_pk_mov_b32 v[74:75], v[70:71], v[72:73] op_sel:[1,0]
	v_mov_b32_e32 v71, v73
	v_pk_add_f32 v[70:71], v[74:75], v[70:71]
	s_nop 0
	v_add_f32_e32 v34, v70, v71
	v_fmamk_f32 v34, v34, 0x3b800000, v153
	v_cmp_gt_f32_e32 vcc, s16, v34
	v_mul_f32_e32 v70, 0x4f800000, v34
	s_nop 0
	v_cndmask_b32_e32 v34, v34, v70, vcc
	v_sqrt_f32_e32 v70, v34
	s_nop 0
	v_add_u32_e32 v71, -1, v70
	v_fma_f32 v72, -v71, v70, v34
	v_cmp_ge_f32_e64 s[6:7], 0, v72
	v_add_u32_e32 v72, 1, v70
	s_nop 0
	v_cndmask_b32_e64 v71, v70, v71, s[6:7]
	v_fma_f32 v70, -v72, v70, v34
	v_cmp_lt_f32_e64 s[6:7], 0, v70
	s_nop 1
	v_cndmask_b32_e64 v70, v71, v72, s[6:7]
	v_mul_f32_e32 v71, 0x37800000, v70
	v_cndmask_b32_e32 v70, v70, v71, vcc
	v_cmp_class_f32_e32 vcc, v34, v154
	s_nop 1
	v_cndmask_b32_e32 v34, v70, v34, vcc
	v_div_scale_f32 v70, s[6:7], v34, v34, 1.0
	v_rcp_f32_e32 v71, v70
	s_nop 0
	v_fma_f32 v72, -v70, v71, 1.0
	v_fmac_f32_e32 v71, v72, v71
	v_div_scale_f32 v72, vcc, 1.0, v34, 1.0
	v_mul_f32_e32 v73, v72, v71
	v_fma_f32 v74, -v70, v73, v72
	v_fmac_f32_e32 v73, v74, v71
	v_fma_f32 v70, -v70, v73, v72
	v_div_fmas_f32 v70, v70, v71, v73
	v_div_fixup_f32 v34, v70, v34, 1.0
	v_pk_mul_f32 v[2:3], v[34:35], v[2:3] op_sel_hi:[0,1]
	v_pk_mul_f32 v[18:19], v[34:35], v[18:19] op_sel_hi:[0,1]
	v_pk_mul_f32 v[16:17], v[34:35], v[16:17] op_sel_hi:[0,1]
	v_pk_mul_f32 v[14:15], v[34:35], v[14:15] op_sel_hi:[0,1]
	v_pk_mul_f32 v[12:13], v[34:35], v[12:13] op_sel_hi:[0,1]
	v_pk_mul_f32 v[10:11], v[34:35], v[10:11] op_sel_hi:[0,1]
	v_pk_mul_f32 v[8:9], v[34:35], v[8:9] op_sel_hi:[0,1]
	v_pk_mul_f32 v[6:7], v[34:35], v[6:7] op_sel_hi:[0,1]
	v_pk_mul_f32 v[4:5], v[34:35], v[4:5] op_sel_hi:[0,1]
	v_pk_mul_f32 v[32:33], v[34:35], v[32:33] op_sel_hi:[0,1]
	v_pk_mul_f32 v[30:31], v[34:35], v[30:31] op_sel_hi:[0,1]
	v_pk_mul_f32 v[28:29], v[34:35], v[28:29] op_sel_hi:[0,1]
	v_pk_mul_f32 v[26:27], v[34:35], v[26:27] op_sel_hi:[0,1]
	v_pk_mul_f32 v[24:25], v[34:35], v[24:25] op_sel_hi:[0,1]
	v_pk_mul_f32 v[22:23], v[34:35], v[22:23] op_sel_hi:[0,1]
	v_pk_mul_f32 v[20:21], v[34:35], v[20:21] op_sel_hi:[0,1]
	v_max_f32_e64 v34, |v2|, |v18|
	v_max_f32_e64 v70, |v3|, |v19|
	v_max3_f32 v34, v34, 0, v70
	v_max_f32_e64 v70, |v4|, |v20|
	v_max_f32_e64 v71, |v5|, |v21|
	v_max3_f32 v34, v34, v70, v71
	v_max_f32_e64 v70, |v6|, |v22|
	v_max_f32_e64 v71, |v7|, |v23|
	v_max3_f32 v34, v34, v70, v71
	v_max_f32_e64 v70, |v8|, |v24|
	v_max_f32_e64 v71, |v9|, |v25|
	v_max3_f32 v34, v34, v70, v71
	v_max_f32_e64 v70, |v10|, |v26|
	v_max_f32_e64 v71, |v11|, |v27|
	v_max3_f32 v34, v34, v70, v71
	v_max_f32_e64 v70, |v12|, |v28|
	v_max_f32_e64 v71, |v13|, |v29|
	v_max3_f32 v34, v34, v70, v71
	v_max_f32_e64 v70, |v14|, |v30|
	v_max_f32_e64 v71, |v15|, |v31|
	v_max3_f32 v34, v34, v70, v71
	v_max_f32_e64 v70, |v16|, |v32|
	v_max_f32_e64 v71, |v17|, |v33|
	v_max3_f32 v34, v34, v70, v71
	v_bfe_u32 v70, v34, 23, 8
	v_and_b32_e32 v34, 0x7fffff, v34
	v_cmp_gt_u32_e32 vcc, s17, v34
	s_nop 1
	v_cndmask_b32_e64 v34, -2, -3, vcc
	v_add3_u32 v34, v70, v34, s2
	v_max_i32_e32 v34, 0xffffff88, v34
	v_add_u32_e32 v34, 0x7f, v34
	v_lshlrev_b32_e32 v76, 23, v34
	v_cvt_scalef32_2xpk16_fp6_f32 v[70:75], v[2:17], v[18:33], v76
	v_lshlrev_b64 v[2:3], 10, v[68:69]
	v_lshl_add_u64 v[2:3], s[22:23], 0, v[2:3]
	v_lshl_add_u64 v[2:3], v[2:3], 0, s[88:89]
	v_add_u32_e32 v68, 0x80, v68
	v_mul_lo_u32 v34, v34, s40
	v_lshl_add_u64 v[2:3], v[2:3], 0, s[26:27]
	v_mov_b32_e32 v32, v74
	v_mov_b32_e32 v33, v75
	v_ashrrev_i32_e32 v69, 31, v68
	global_store_dwordx4 v[2:3], v[70:73], off
	global_store_dwordx4 v[2:3], v[32:35], off offset:16
	v_lshlrev_b64 v[2:3], 5, v[68:69]
	v_lshl_add_u64 v[2:3], s[18:19], 0, v[2:3]
	global_load_dwordx4 v[4:7], v[2:3], off
	global_load_dwordx4 v[8:11], v[2:3], off offset:16
	s_waitcnt vmcnt(0)
	v_pk_add_f32 v[2:3], v[6:7], v[10:11]
	v_pk_add_f32 v[4:5], v[4:5], v[8:9]
	s_nop 0
	v_pk_mov_b32 v[6:7], v[4:5], v[2:3] op_sel:[1,0]
	v_mov_b32_e32 v5, v3
	v_pk_add_f32 v[2:3], v[6:7], v[4:5]
	s_nop 0
	v_add_f32_e32 v2, v2, v3
	v_fmamk_f32 v2, v2, 0x3b800000, v153
	v_cmp_gt_f32_e32 vcc, s16, v2
	v_mul_f32_e32 v3, 0x4f800000, v2
	s_nop 0
	v_cndmask_b32_e32 v2, v2, v3, vcc
	v_sqrt_f32_e32 v3, v2
	s_nop 0
	v_add_u32_e32 v4, -1, v3
	v_fma_f32 v5, -v4, v3, v2
	v_cmp_ge_f32_e64 s[6:7], 0, v5
	v_add_u32_e32 v5, 1, v3
	s_nop 0
	v_cndmask_b32_e64 v4, v3, v4, s[6:7]
	v_fma_f32 v3, -v5, v3, v2
	v_cmp_lt_f32_e64 s[6:7], 0, v3
	s_nop 1
	v_cndmask_b32_e64 v3, v4, v5, s[6:7]
	v_mul_f32_e32 v4, 0x37800000, v3
	v_cndmask_b32_e32 v3, v3, v4, vcc
	v_cmp_class_f32_e32 vcc, v2, v154
	s_nop 1
	v_cndmask_b32_e32 v2, v3, v2, vcc
	v_div_scale_f32 v3, s[6:7], v2, v2, 1.0
	v_rcp_f32_e32 v4, v3
	s_mov_b64 s[6:7], -1
	v_fma_f32 v5, -v3, v4, 1.0
	v_fmac_f32_e32 v4, v5, v4
	v_div_scale_f32 v5, vcc, 1.0, v2, 1.0
	v_mul_f32_e32 v6, v5, v4
	v_fma_f32 v7, -v3, v6, v5
	v_fmac_f32_e32 v6, v7, v4
	v_fma_f32 v3, -v3, v6, v5
	v_div_fmas_f32 v3, v3, v4, v6
	v_div_fixup_f32 v18, v3, v2, 1.0
	v_pk_mul_f32 v[16:17], v[18:19], v[62:63] op_sel_hi:[0,1]
	v_pk_mul_f32 v[14:15], v[18:19], v[60:61] op_sel_hi:[0,1]
	v_pk_mul_f32 v[12:13], v[18:19], v[54:55] op_sel_hi:[0,1]
	v_pk_mul_f32 v[10:11], v[18:19], v[52:53] op_sel_hi:[0,1]
	v_pk_mul_f32 v[8:9], v[18:19], v[46:47] op_sel_hi:[0,1]
	v_pk_mul_f32 v[6:7], v[18:19], v[44:45] op_sel_hi:[0,1]
	v_pk_mul_f32 v[4:5], v[18:19], v[38:39] op_sel_hi:[0,1]
	v_pk_mul_f32 v[2:3], v[18:19], v[36:37] op_sel_hi:[0,1]
	v_pk_mul_f32 v[32:33], v[18:19], v[66:67] op_sel_hi:[0,1]
	v_pk_mul_f32 v[30:31], v[18:19], v[64:65] op_sel_hi:[0,1]
	v_pk_mul_f32 v[28:29], v[18:19], v[58:59] op_sel_hi:[0,1]
	v_pk_mul_f32 v[26:27], v[18:19], v[56:57] op_sel_hi:[0,1]
	v_pk_mul_f32 v[24:25], v[18:19], v[50:51] op_sel_hi:[0,1]
	v_pk_mul_f32 v[22:23], v[18:19], v[48:49] op_sel_hi:[0,1]
	v_pk_mul_f32 v[20:21], v[18:19], v[42:43] op_sel_hi:[0,1]
	v_pk_mul_f32 v[18:19], v[18:19], v[40:41] op_sel_hi:[0,1]
	v_max_f32_e64 v34, |v2|, |v18|
	v_max_f32_e64 v36, |v3|, |v19|
	v_max3_f32 v34, v34, 0, v36
	v_max_f32_e64 v36, |v4|, |v20|
	v_max_f32_e64 v37, |v5|, |v21|
	v_max3_f32 v34, v34, v36, v37
	v_max_f32_e64 v36, |v6|, |v22|
	v_max_f32_e64 v37, |v7|, |v23|
	v_max3_f32 v34, v34, v36, v37
	v_max_f32_e64 v36, |v8|, |v24|
	v_max_f32_e64 v37, |v9|, |v25|
	v_max3_f32 v34, v34, v36, v37
	v_max_f32_e64 v36, |v10|, |v26|
	v_max_f32_e64 v37, |v11|, |v27|
	v_max3_f32 v34, v34, v36, v37
	v_max_f32_e64 v36, |v12|, |v28|
	v_max_f32_e64 v37, |v13|, |v29|
	v_max3_f32 v34, v34, v36, v37
	v_max_f32_e64 v36, |v14|, |v30|
	v_max_f32_e64 v37, |v15|, |v31|
	v_max3_f32 v34, v34, v36, v37
	v_max_f32_e64 v36, |v16|, |v32|
	v_max_f32_e64 v37, |v17|, |v33|
	v_max3_f32 v34, v34, v36, v37
	v_bfe_u32 v36, v34, 23, 8
	v_and_b32_e32 v34, 0x7fffff, v34
	v_cmp_gt_u32_e32 vcc, s17, v34
	s_nop 1
	v_cndmask_b32_e64 v34, -2, -3, vcc
	v_add3_u32 v34, v36, v34, s2
	v_max_i32_e32 v34, 0xffffff88, v34
	v_add_u32_e32 v34, 0x7f, v34
	v_lshlrev_b32_e32 v42, 23, v34
	v_cvt_scalef32_2xpk16_fp6_f32 v[36:41], v[2:17], v[18:33], v42
	v_lshlrev_b64 v[2:3], 10, v[68:69]
	v_lshl_add_u64 v[2:3], s[22:23], 0, v[2:3]
	v_lshl_add_u64 v[2:3], v[2:3], 0, s[88:89]
	v_mul_lo_u32 v34, v34, s40
	v_lshl_add_u64 v[2:3], v[2:3], 0, s[26:27]
	v_mov_b32_e32 v32, v40
	v_mov_b32_e32 v33, v41
	global_store_dwordx4 v[2:3], v[36:39], off
	global_store_dwordx4 v[2:3], v[32:35], off offset:16
	s_cbranch_scc1 .LBB0_1649
	v_readlane_b32 s6, v254, 50
	v_readlane_b32 s7, v254, 51
	s_andn2_b64 vcc, exec, s[6:7]
	s_cbranch_vccnz .LBB0_1648
	s_barrier
	s_branch .LBB0_1648
